# fused residual stages: per-row counted vmcnt waits (row k waits only for its own two x loads) instead of vmcnt(0) before the first element
# baseline (speedup 1.0000x reference)
.LBB0_852:
	s_or_b64 exec, exec, s[0:1]
	s_waitcnt lgkmcnt(0)
	s_barrier
	s_and_b32 s98, s2, 7
	s_lshl_b32 s98, s98, 3
	s_bfe_u32 s99, s2, 0x30003
	s_or_b32 s98, s98, s99
	s_lshr_b32 s99, s2, 6
	v_and_b32_e32 v172, 0xff, v136
	v_lshrrev_b32_e32 v173, 8, v136
	v_mul_u32_u24_e32 v173, 0x84000, v173
	v_lshl_add_u32 v172, v172, 2, v173
	s_lshl_b32 s24, s98, 10
	s_add_u32 s18, s44, s24
	s_addc_u32 s19, s45, 0
	global_load_dword v164, v172, s[18:19]
	s_add_u32 s18, s18, 0x10800
	s_addc_u32 s19, s19, 0
	global_load_dword v165, v172, s[18:19]
	s_add_u32 s18, s18, 0x10800
	s_addc_u32 s19, s19, 0
	global_load_dword v166, v172, s[18:19]
	s_add_u32 s18, s18, 0x10800
	s_addc_u32 s19, s19, 0
	global_load_dword v167, v172, s[18:19]
	s_add_u32 s18, s18, 0x10800
	s_addc_u32 s19, s19, 0
	global_load_dword v168, v172, s[18:19]
	s_add_u32 s18, s18, 0x10800
	s_addc_u32 s19, s19, 0
	global_load_dword v169, v172, s[18:19]
	s_add_u32 s18, s18, 0x10800
	s_addc_u32 s19, s19, 0
	global_load_dword v170, v172, s[18:19]
	s_add_u32 s18, s18, 0x10800
	s_addc_u32 s19, s19, 0
	global_load_dword v171, v172, s[18:19]
	v_lshrrev_b32_e32 v141, 8, v136
	v_and_b32_e32 v142, 15, v136
	v_lshl_add_u32 v141, v141, 6, v142
	v_bfe_u32 v144, v136, 6, 2
	v_bfe_u32 v145, v136, 4, 2
	v_lshlrev_b32_e32 v144, 5, v144
	v_lshl_add_u32 v144, v145, 3, v144
	s_lshl_b32 s24, s99, 8
	v_add_u32_e32 v144, s24, v144
	s_lshl_b32 s25, s98, 8
	v_add_u32_e32 v145, s25, v141
	v_lshl_add_u32 v146, v145, 10, v144
	v_lshlrev_b32_e32 v140, 1, v146
	v_lshlrev_b32_e32 v147, 2, v144
	v_readlane_b32 s18, v253, 3
	v_readlane_b32 s19, v253, 4
	v_readlane_b32 s20, v253, 53
	v_readlane_b32 s21, v253, 54
	s_nop 4
	s_add_u32 s18, s18, 0x1000
	s_addc_u32 s19, s19, 0
	global_load_dwordx4 v[148:151], v147, s[18:19]
	global_load_dwordx4 v[152:155], v147, s[18:19] offset:16
	global_load_dwordx4 v[156:159], v147, s[18:19] offset:512
	global_load_dwordx4 v[160:163], v147, s[18:19] offset:528
	s_add_u32 s22, s20, 0x0
	s_addc_u32 s23, s21, 0
	global_load_dwordx4 v[188:191], v140, s[22:23] nt
	global_load_dwordx4 v[192:195], v140, s[22:23] offset:256 nt
	s_add_u32 s22, s20, 0x8000
	s_addc_u32 s23, s21, 0
	global_load_dwordx4 v[196:199], v140, s[22:23] nt
	global_load_dwordx4 v[200:203], v140, s[22:23] offset:256 nt
	s_add_u32 s22, s20, 0x10000
	s_addc_u32 s23, s21, 0
	global_load_dwordx4 v[204:207], v140, s[22:23] nt
	global_load_dwordx4 v[208:211], v140, s[22:23] offset:256 nt
	s_add_u32 s22, s20, 0x18000
	s_addc_u32 s23, s21, 0
	global_load_dwordx4 v[212:215], v140, s[22:23] nt
	global_load_dwordx4 v[216:219], v140, s[22:23] offset:256 nt
	s_add_u32 s22, s20, 0x40000
	s_addc_u32 s23, s21, 0
	global_load_dwordx4 v[220:223], v140, s[22:23] nt
	global_load_dwordx4 v[224:227], v140, s[22:23] offset:256 nt
	s_add_u32 s22, s20, 0x48000
	s_addc_u32 s23, s21, 0
	global_load_dwordx4 v[228:231], v140, s[22:23] nt
	global_load_dwordx4 v[232:235], v140, s[22:23] offset:256 nt
	s_add_u32 s22, s20, 0x50000
	s_addc_u32 s23, s21, 0
	global_load_dwordx4 v[236:239], v140, s[22:23] nt
	global_load_dwordx4 v[240:243], v140, s[22:23] offset:256 nt
	s_add_u32 s22, s20, 0x58000
	s_addc_u32 s23, s21, 0
	global_load_dwordx4 v[244:247], v140, s[22:23] nt
	global_load_dwordx4 v[248:251], v140, s[22:23] offset:256 nt
	s_waitcnt vmcnt(20)
	v_add_f32_e32 v164, v164, v165
	v_add_f32_e32 v164, v164, v166
	v_add_f32_e32 v164, v164, v167
	v_add_f32_e32 v164, v164, v168
	v_add_f32_e32 v164, v164, v169
	v_add_f32_e32 v164, v164, v170
	v_add_f32_e32 v164, v164, v171
	v_lshlrev_b32_e32 v173, 2, v136
	ds_write_b32 v173, v164
	s_waitcnt lgkmcnt(0)
	s_barrier
	v_lshlrev_b32_e32 v142, 2, v141
	ds_read_b32 v128, v142 offset:0
	ds_read_b32 v174, v142 offset:1024
	ds_read_b32 v129, v142 offset:64
	ds_read_b32 v175, v142 offset:1088
	ds_read_b32 v130, v142 offset:128
	ds_read_b32 v176, v142 offset:1152
	ds_read_b32 v131, v142 offset:192
	ds_read_b32 v177, v142 offset:1216
	ds_read_b32 v132, v142 offset:512
	ds_read_b32 v178, v142 offset:1536
	ds_read_b32 v133, v142 offset:576
	ds_read_b32 v179, v142 offset:1600
	ds_read_b32 v134, v142 offset:640
	ds_read_b32 v180, v142 offset:1664
	ds_read_b32 v135, v142 offset:704
	ds_read_b32 v181, v142 offset:1728
	s_waitcnt lgkmcnt(0)
	s_mov_b32 s101, 0x3a800000
	v_mov_b32_e32 v143, 0x358637bd
	v_add_f32_e32 v128, v128, v174
	v_add_f32_e32 v129, v129, v175
	v_add_f32_e32 v130, v130, v176
	v_add_f32_e32 v131, v131, v177
	v_add_f32_e32 v132, v132, v178
	v_add_f32_e32 v133, v133, v179
	v_add_f32_e32 v134, v134, v180
	v_add_f32_e32 v135, v135, v181
	v_fma_f32 v128, v128, s101, v143
	v_fma_f32 v129, v129, s101, v143
	v_fma_f32 v130, v130, s101, v143
	v_fma_f32 v131, v131, s101, v143
	v_fma_f32 v132, v132, s101, v143
	v_fma_f32 v133, v133, s101, v143
	v_fma_f32 v134, v134, s101, v143
	v_fma_f32 v135, v135, s101, v143
	v_rsq_f32_e32 v128, v128
	v_rsq_f32_e32 v129, v129
	v_rsq_f32_e32 v130, v130
	v_rsq_f32_e32 v131, v131
	v_rsq_f32_e32 v132, v132
	v_rsq_f32_e32 v133, v133
	v_rsq_f32_e32 v134, v134
	v_rsq_f32_e32 v135, v135
	s_add_u32 s22, s60, 0x0
	s_addc_u32 s23, s61, 0
	s_waitcnt vmcnt(14)
	v_lshlrev_b32_e32 v164, 16, v188
	v_and_b32_e32 v165, 0xffff0000, v188
	v_lshlrev_b32_e32 v166, 16, v189
	v_and_b32_e32 v167, 0xffff0000, v189
	v_lshlrev_b32_e32 v168, 16, v190
	v_and_b32_e32 v169, 0xffff0000, v190
	v_lshlrev_b32_e32 v170, 16, v191
	v_and_b32_e32 v171, 0xffff0000, v191
	v_pk_mul_f32 v[124:125], v[124:125], v[128:129] op_sel_hi:[1,0]
	v_pk_mul_f32 v[126:127], v[126:127], v[128:129] op_sel_hi:[1,0]
	v_pk_mul_f32 v[112:113], v[112:113], v[128:129] op_sel_hi:[1,0]
	v_pk_mul_f32 v[114:115], v[114:115], v[128:129] op_sel_hi:[1,0]
	v_pk_fma_f32 v[164:165], v[124:125], v[148:149], v[164:165]
	v_pk_fma_f32 v[166:167], v[126:127], v[150:151], v[166:167]
	v_pk_fma_f32 v[168:169], v[112:113], v[152:153], v[168:169]
	v_pk_fma_f32 v[170:171], v[114:115], v[154:155], v[170:171]
	v_mul_f32_e32 v138, v164, v164
	v_fmac_f32_e32 v138, v165, v165
	v_fmac_f32_e32 v138, v166, v166
	v_fmac_f32_e32 v138, v167, v167
	v_fmac_f32_e32 v138, v168, v168
	v_fmac_f32_e32 v138, v169, v169
	v_fmac_f32_e32 v138, v170, v170
	v_fmac_f32_e32 v138, v171, v171
	v_cvt_pk_bf16_f32 v180, v164, v165
	v_cvt_pk_bf16_f32 v181, v166, v167
	v_cvt_pk_bf16_f32 v182, v168, v169
	v_cvt_pk_bf16_f32 v183, v170, v171
	global_store_dwordx4 v140, v[180:183], s[22:23]
	v_lshlrev_b32_e32 v172, 16, v192
	v_and_b32_e32 v173, 0xffff0000, v192
	v_lshlrev_b32_e32 v174, 16, v193
	v_and_b32_e32 v175, 0xffff0000, v193
	v_lshlrev_b32_e32 v176, 16, v194
	v_and_b32_e32 v177, 0xffff0000, v194
	v_lshlrev_b32_e32 v178, 16, v195
	v_and_b32_e32 v179, 0xffff0000, v195
	v_pk_mul_f32 v[120:121], v[120:121], v[128:129] op_sel_hi:[1,0]
	v_pk_mul_f32 v[122:123], v[122:123], v[128:129] op_sel_hi:[1,0]
	v_pk_mul_f32 v[116:117], v[116:117], v[128:129] op_sel_hi:[1,0]
	v_pk_mul_f32 v[118:119], v[118:119], v[128:129] op_sel_hi:[1,0]
	v_pk_fma_f32 v[172:173], v[120:121], v[156:157], v[172:173]
	v_pk_fma_f32 v[174:175], v[122:123], v[158:159], v[174:175]
	v_pk_fma_f32 v[176:177], v[116:117], v[160:161], v[176:177]
	v_pk_fma_f32 v[178:179], v[118:119], v[162:163], v[178:179]
	v_fmac_f32_e32 v138, v172, v172
	v_fmac_f32_e32 v138, v173, v173
	v_fmac_f32_e32 v138, v174, v174
	v_fmac_f32_e32 v138, v175, v175
	v_fmac_f32_e32 v138, v176, v176
	v_fmac_f32_e32 v138, v177, v177
	v_fmac_f32_e32 v138, v178, v178
	v_fmac_f32_e32 v138, v179, v179
	v_cvt_pk_bf16_f32 v184, v172, v173
	v_cvt_pk_bf16_f32 v185, v174, v175
	v_cvt_pk_bf16_f32 v186, v176, v177
	v_cvt_pk_bf16_f32 v187, v178, v179
	global_store_dwordx4 v140, v[184:187], s[22:23] offset:256
	s_add_u32 s22, s60, 0x8000
	s_addc_u32 s23, s61, 0
	s_waitcnt vmcnt(14)
	v_lshlrev_b32_e32 v164, 16, v196
	v_and_b32_e32 v165, 0xffff0000, v196
	v_lshlrev_b32_e32 v166, 16, v197
	v_and_b32_e32 v167, 0xffff0000, v197
	v_lshlrev_b32_e32 v168, 16, v198
	v_and_b32_e32 v169, 0xffff0000, v198
	v_lshlrev_b32_e32 v170, 16, v199
	v_and_b32_e32 v171, 0xffff0000, v199
	v_pk_mul_f32 v[108:109], v[108:109], v[128:129] op_sel:[0,1] op_sel_hi:[1,1]
	v_pk_mul_f32 v[110:111], v[110:111], v[128:129] op_sel:[0,1] op_sel_hi:[1,1]
	v_pk_mul_f32 v[96:97], v[96:97], v[128:129] op_sel:[0,1] op_sel_hi:[1,1]
	v_pk_mul_f32 v[98:99], v[98:99], v[128:129] op_sel:[0,1] op_sel_hi:[1,1]
	v_pk_fma_f32 v[164:165], v[108:109], v[148:149], v[164:165]
	v_pk_fma_f32 v[166:167], v[110:111], v[150:151], v[166:167]
	v_pk_fma_f32 v[168:169], v[96:97], v[152:153], v[168:169]
	v_pk_fma_f32 v[170:171], v[98:99], v[154:155], v[170:171]
	v_mul_f32_e32 v139, v164, v164
	v_fmac_f32_e32 v139, v165, v165
	v_fmac_f32_e32 v139, v166, v166
	v_fmac_f32_e32 v139, v167, v167
	v_fmac_f32_e32 v139, v168, v168
	v_fmac_f32_e32 v139, v169, v169
	v_fmac_f32_e32 v139, v170, v170
	v_fmac_f32_e32 v139, v171, v171
	v_cvt_pk_bf16_f32 v180, v164, v165
	v_cvt_pk_bf16_f32 v181, v166, v167
	v_cvt_pk_bf16_f32 v182, v168, v169
	v_cvt_pk_bf16_f32 v183, v170, v171
	global_store_dwordx4 v140, v[180:183], s[22:23]
	v_lshlrev_b32_e32 v172, 16, v200
	v_and_b32_e32 v173, 0xffff0000, v200
	v_lshlrev_b32_e32 v174, 16, v201
	v_and_b32_e32 v175, 0xffff0000, v201
	v_lshlrev_b32_e32 v176, 16, v202
	v_and_b32_e32 v177, 0xffff0000, v202
	v_lshlrev_b32_e32 v178, 16, v203
	v_and_b32_e32 v179, 0xffff0000, v203
	v_pk_mul_f32 v[100:101], v[100:101], v[128:129] op_sel:[0,1] op_sel_hi:[1,1]
	v_pk_mul_f32 v[102:103], v[102:103], v[128:129] op_sel:[0,1] op_sel_hi:[1,1]
	v_pk_mul_f32 v[104:105], v[104:105], v[128:129] op_sel:[0,1] op_sel_hi:[1,1]
	v_pk_mul_f32 v[106:107], v[106:107], v[128:129] op_sel:[0,1] op_sel_hi:[1,1]
	v_pk_fma_f32 v[172:173], v[100:101], v[156:157], v[172:173]
	v_pk_fma_f32 v[174:175], v[102:103], v[158:159], v[174:175]
	v_pk_fma_f32 v[176:177], v[104:105], v[160:161], v[176:177]
	v_pk_fma_f32 v[178:179], v[106:107], v[162:163], v[178:179]
	v_fmac_f32_e32 v139, v172, v172
	v_fmac_f32_e32 v139, v173, v173
	v_fmac_f32_e32 v139, v174, v174
	v_fmac_f32_e32 v139, v175, v175
	v_fmac_f32_e32 v139, v176, v176
	v_fmac_f32_e32 v139, v177, v177
	v_fmac_f32_e32 v139, v178, v178
	v_fmac_f32_e32 v139, v179, v179
	v_cvt_pk_bf16_f32 v184, v172, v173
	v_cvt_pk_bf16_f32 v185, v174, v175
	v_cvt_pk_bf16_f32 v186, v176, v177
	v_cvt_pk_bf16_f32 v187, v178, v179
	global_store_dwordx4 v140, v[184:187], s[22:23] offset:256
	s_add_u32 s22, s60, 0x10000
	s_addc_u32 s23, s61, 0
	s_waitcnt vmcnt(14)
	v_lshlrev_b32_e32 v164, 16, v204
	v_and_b32_e32 v165, 0xffff0000, v204
	v_lshlrev_b32_e32 v166, 16, v205
	v_and_b32_e32 v167, 0xffff0000, v205
	v_lshlrev_b32_e32 v168, 16, v206
	v_and_b32_e32 v169, 0xffff0000, v206
	v_lshlrev_b32_e32 v170, 16, v207
	v_and_b32_e32 v171, 0xffff0000, v207
	v_pk_mul_f32 v[92:93], v[92:93], v[130:131] op_sel_hi:[1,0]
	v_pk_mul_f32 v[94:95], v[94:95], v[130:131] op_sel_hi:[1,0]
	v_pk_mul_f32 v[80:81], v[80:81], v[130:131] op_sel_hi:[1,0]
	v_pk_mul_f32 v[82:83], v[82:83], v[130:131] op_sel_hi:[1,0]
	v_pk_fma_f32 v[164:165], v[92:93], v[148:149], v[164:165]
	v_pk_fma_f32 v[166:167], v[94:95], v[150:151], v[166:167]
	v_pk_fma_f32 v[168:169], v[80:81], v[152:153], v[168:169]
	v_pk_fma_f32 v[170:171], v[82:83], v[154:155], v[170:171]
	v_mul_f32_e32 v141, v164, v164
	v_fmac_f32_e32 v141, v165, v165
	v_fmac_f32_e32 v141, v166, v166
	v_fmac_f32_e32 v141, v167, v167
	v_fmac_f32_e32 v141, v168, v168
	v_fmac_f32_e32 v141, v169, v169
	v_fmac_f32_e32 v141, v170, v170
	v_fmac_f32_e32 v141, v171, v171
	v_cvt_pk_bf16_f32 v180, v164, v165
	v_cvt_pk_bf16_f32 v181, v166, v167
	v_cvt_pk_bf16_f32 v182, v168, v169
	v_cvt_pk_bf16_f32 v183, v170, v171
	global_store_dwordx4 v140, v[180:183], s[22:23]
	v_lshlrev_b32_e32 v172, 16, v208
	v_and_b32_e32 v173, 0xffff0000, v208
	v_lshlrev_b32_e32 v174, 16, v209
	v_and_b32_e32 v175, 0xffff0000, v209
	v_lshlrev_b32_e32 v176, 16, v210
	v_and_b32_e32 v177, 0xffff0000, v210
	v_lshlrev_b32_e32 v178, 16, v211
	v_and_b32_e32 v179, 0xffff0000, v211
	v_pk_mul_f32 v[84:85], v[84:85], v[130:131] op_sel_hi:[1,0]
	v_pk_mul_f32 v[86:87], v[86:87], v[130:131] op_sel_hi:[1,0]
	v_pk_mul_f32 v[88:89], v[88:89], v[130:131] op_sel_hi:[1,0]
	v_pk_mul_f32 v[90:91], v[90:91], v[130:131] op_sel_hi:[1,0]
	v_pk_fma_f32 v[172:173], v[84:85], v[156:157], v[172:173]
	v_pk_fma_f32 v[174:175], v[86:87], v[158:159], v[174:175]
	v_pk_fma_f32 v[176:177], v[88:89], v[160:161], v[176:177]
	v_pk_fma_f32 v[178:179], v[90:91], v[162:163], v[178:179]
	v_fmac_f32_e32 v141, v172, v172
	v_fmac_f32_e32 v141, v173, v173
	v_fmac_f32_e32 v141, v174, v174
	v_fmac_f32_e32 v141, v175, v175
	v_fmac_f32_e32 v141, v176, v176
	v_fmac_f32_e32 v141, v177, v177
	v_fmac_f32_e32 v141, v178, v178
	v_fmac_f32_e32 v141, v179, v179
	v_cvt_pk_bf16_f32 v184, v172, v173
	v_cvt_pk_bf16_f32 v185, v174, v175
	v_cvt_pk_bf16_f32 v186, v176, v177
	v_cvt_pk_bf16_f32 v187, v178, v179
	global_store_dwordx4 v140, v[184:187], s[22:23] offset:256
	s_add_u32 s22, s60, 0x18000
	s_addc_u32 s23, s61, 0
	s_waitcnt vmcnt(14)
	v_lshlrev_b32_e32 v164, 16, v212
	v_and_b32_e32 v165, 0xffff0000, v212
	v_lshlrev_b32_e32 v166, 16, v213
	v_and_b32_e32 v167, 0xffff0000, v213
	v_lshlrev_b32_e32 v168, 16, v214
	v_and_b32_e32 v169, 0xffff0000, v214
	v_lshlrev_b32_e32 v170, 16, v215
	v_and_b32_e32 v171, 0xffff0000, v215
	v_pk_mul_f32 v[76:77], v[76:77], v[130:131] op_sel:[0,1] op_sel_hi:[1,1]
	v_pk_mul_f32 v[78:79], v[78:79], v[130:131] op_sel:[0,1] op_sel_hi:[1,1]
	v_pk_mul_f32 v[64:65], v[64:65], v[130:131] op_sel:[0,1] op_sel_hi:[1,1]
	v_pk_mul_f32 v[66:67], v[66:67], v[130:131] op_sel:[0,1] op_sel_hi:[1,1]
	v_pk_fma_f32 v[164:165], v[76:77], v[148:149], v[164:165]
	v_pk_fma_f32 v[166:167], v[78:79], v[150:151], v[166:167]
	v_pk_fma_f32 v[168:169], v[64:65], v[152:153], v[168:169]
	v_pk_fma_f32 v[170:171], v[66:67], v[154:155], v[170:171]
	v_mul_f32_e32 v142, v164, v164
	v_fmac_f32_e32 v142, v165, v165
	v_fmac_f32_e32 v142, v166, v166
	v_fmac_f32_e32 v142, v167, v167
	v_fmac_f32_e32 v142, v168, v168
	v_fmac_f32_e32 v142, v169, v169
	v_fmac_f32_e32 v142, v170, v170
	v_fmac_f32_e32 v142, v171, v171
	v_cvt_pk_bf16_f32 v180, v164, v165
	v_cvt_pk_bf16_f32 v181, v166, v167
	v_cvt_pk_bf16_f32 v182, v168, v169
	v_cvt_pk_bf16_f32 v183, v170, v171
	global_store_dwordx4 v140, v[180:183], s[22:23]
	v_lshlrev_b32_e32 v172, 16, v216
	v_and_b32_e32 v173, 0xffff0000, v216
	v_lshlrev_b32_e32 v174, 16, v217
	v_and_b32_e32 v175, 0xffff0000, v217
	v_lshlrev_b32_e32 v176, 16, v218
	v_and_b32_e32 v177, 0xffff0000, v218
	v_lshlrev_b32_e32 v178, 16, v219
	v_and_b32_e32 v179, 0xffff0000, v219
	v_pk_mul_f32 v[68:69], v[68:69], v[130:131] op_sel:[0,1] op_sel_hi:[1,1]
	v_pk_mul_f32 v[70:71], v[70:71], v[130:131] op_sel:[0,1] op_sel_hi:[1,1]
	v_pk_mul_f32 v[72:73], v[72:73], v[130:131] op_sel:[0,1] op_sel_hi:[1,1]
	v_pk_mul_f32 v[74:75], v[74:75], v[130:131] op_sel:[0,1] op_sel_hi:[1,1]
	v_pk_fma_f32 v[172:173], v[68:69], v[156:157], v[172:173]
	v_pk_fma_f32 v[174:175], v[70:71], v[158:159], v[174:175]
	v_pk_fma_f32 v[176:177], v[72:73], v[160:161], v[176:177]
	v_pk_fma_f32 v[178:179], v[74:75], v[162:163], v[178:179]
	v_fmac_f32_e32 v142, v172, v172
	v_fmac_f32_e32 v142, v173, v173
	v_fmac_f32_e32 v142, v174, v174
	v_fmac_f32_e32 v142, v175, v175
	v_fmac_f32_e32 v142, v176, v176
	v_fmac_f32_e32 v142, v177, v177
	v_fmac_f32_e32 v142, v178, v178
	v_fmac_f32_e32 v142, v179, v179
	v_cvt_pk_bf16_f32 v184, v172, v173
	v_cvt_pk_bf16_f32 v185, v174, v175
	v_cvt_pk_bf16_f32 v186, v176, v177
	v_cvt_pk_bf16_f32 v187, v178, v179
	global_store_dwordx4 v140, v[184:187], s[22:23] offset:256
	s_add_u32 s22, s60, 0x40000
	s_addc_u32 s23, s61, 0
	s_waitcnt vmcnt(14)
	v_lshlrev_b32_e32 v164, 16, v220
	v_and_b32_e32 v165, 0xffff0000, v220
	v_lshlrev_b32_e32 v166, 16, v221
	v_and_b32_e32 v167, 0xffff0000, v221
	v_lshlrev_b32_e32 v168, 16, v222
	v_and_b32_e32 v169, 0xffff0000, v222
	v_lshlrev_b32_e32 v170, 16, v223
	v_and_b32_e32 v171, 0xffff0000, v223
	v_pk_mul_f32 v[60:61], v[60:61], v[132:133] op_sel_hi:[1,0]
	v_pk_mul_f32 v[62:63], v[62:63], v[132:133] op_sel_hi:[1,0]
	v_pk_mul_f32 v[48:49], v[48:49], v[132:133] op_sel_hi:[1,0]
	v_pk_mul_f32 v[50:51], v[50:51], v[132:133] op_sel_hi:[1,0]
	v_pk_fma_f32 v[164:165], v[60:61], v[148:149], v[164:165]
	v_pk_fma_f32 v[166:167], v[62:63], v[150:151], v[166:167]
	v_pk_fma_f32 v[168:169], v[48:49], v[152:153], v[168:169]
	v_pk_fma_f32 v[170:171], v[50:51], v[154:155], v[170:171]
	v_mul_f32_e32 v143, v164, v164
	v_fmac_f32_e32 v143, v165, v165
	v_fmac_f32_e32 v143, v166, v166
	v_fmac_f32_e32 v143, v167, v167
	v_fmac_f32_e32 v143, v168, v168
	v_fmac_f32_e32 v143, v169, v169
	v_fmac_f32_e32 v143, v170, v170
	v_fmac_f32_e32 v143, v171, v171
	v_cvt_pk_bf16_f32 v180, v164, v165
	v_cvt_pk_bf16_f32 v181, v166, v167
	v_cvt_pk_bf16_f32 v182, v168, v169
	v_cvt_pk_bf16_f32 v183, v170, v171
	global_store_dwordx4 v140, v[180:183], s[22:23]
	v_lshlrev_b32_e32 v172, 16, v224
	v_and_b32_e32 v173, 0xffff0000, v224
	v_lshlrev_b32_e32 v174, 16, v225
	v_and_b32_e32 v175, 0xffff0000, v225
	v_lshlrev_b32_e32 v176, 16, v226
	v_and_b32_e32 v177, 0xffff0000, v226
	v_lshlrev_b32_e32 v178, 16, v227
	v_and_b32_e32 v179, 0xffff0000, v227
	v_pk_mul_f32 v[52:53], v[52:53], v[132:133] op_sel_hi:[1,0]
	v_pk_mul_f32 v[54:55], v[54:55], v[132:133] op_sel_hi:[1,0]
	v_pk_mul_f32 v[56:57], v[56:57], v[132:133] op_sel_hi:[1,0]
	v_pk_mul_f32 v[58:59], v[58:59], v[132:133] op_sel_hi:[1,0]
	v_pk_fma_f32 v[172:173], v[52:53], v[156:157], v[172:173]
	v_pk_fma_f32 v[174:175], v[54:55], v[158:159], v[174:175]
	v_pk_fma_f32 v[176:177], v[56:57], v[160:161], v[176:177]
	v_pk_fma_f32 v[178:179], v[58:59], v[162:163], v[178:179]
	v_fmac_f32_e32 v143, v172, v172
	v_fmac_f32_e32 v143, v173, v173
	v_fmac_f32_e32 v143, v174, v174
	v_fmac_f32_e32 v143, v175, v175
	v_fmac_f32_e32 v143, v176, v176
	v_fmac_f32_e32 v143, v177, v177
	v_fmac_f32_e32 v143, v178, v178
	v_fmac_f32_e32 v143, v179, v179
	v_cvt_pk_bf16_f32 v184, v172, v173
	v_cvt_pk_bf16_f32 v185, v174, v175
	v_cvt_pk_bf16_f32 v186, v176, v177
	v_cvt_pk_bf16_f32 v187, v178, v179
	global_store_dwordx4 v140, v[184:187], s[22:23] offset:256
	s_add_u32 s22, s60, 0x48000
	s_addc_u32 s23, s61, 0
	s_waitcnt vmcnt(14)
	v_lshlrev_b32_e32 v164, 16, v228
	v_and_b32_e32 v165, 0xffff0000, v228
	v_lshlrev_b32_e32 v166, 16, v229
	v_and_b32_e32 v167, 0xffff0000, v229
	v_lshlrev_b32_e32 v168, 16, v230
	v_and_b32_e32 v169, 0xffff0000, v230
	v_lshlrev_b32_e32 v170, 16, v231
	v_and_b32_e32 v171, 0xffff0000, v231
	v_pk_mul_f32 v[44:45], v[44:45], v[132:133] op_sel:[0,1] op_sel_hi:[1,1]
	v_pk_mul_f32 v[46:47], v[46:47], v[132:133] op_sel:[0,1] op_sel_hi:[1,1]
	v_pk_mul_f32 v[32:33], v[32:33], v[132:133] op_sel:[0,1] op_sel_hi:[1,1]
	v_pk_mul_f32 v[34:35], v[34:35], v[132:133] op_sel:[0,1] op_sel_hi:[1,1]
	v_pk_fma_f32 v[164:165], v[44:45], v[148:149], v[164:165]
	v_pk_fma_f32 v[166:167], v[46:47], v[150:151], v[166:167]
	v_pk_fma_f32 v[168:169], v[32:33], v[152:153], v[168:169]
	v_pk_fma_f32 v[170:171], v[34:35], v[154:155], v[170:171]
	v_mul_f32_e32 v144, v164, v164
	v_fmac_f32_e32 v144, v165, v165
	v_fmac_f32_e32 v144, v166, v166
	v_fmac_f32_e32 v144, v167, v167
	v_fmac_f32_e32 v144, v168, v168
	v_fmac_f32_e32 v144, v169, v169
	v_fmac_f32_e32 v144, v170, v170
	v_fmac_f32_e32 v144, v171, v171
	v_cvt_pk_bf16_f32 v180, v164, v165
	v_cvt_pk_bf16_f32 v181, v166, v167
	v_cvt_pk_bf16_f32 v182, v168, v169
	v_cvt_pk_bf16_f32 v183, v170, v171
	global_store_dwordx4 v140, v[180:183], s[22:23]
	v_lshlrev_b32_e32 v172, 16, v232
	v_and_b32_e32 v173, 0xffff0000, v232
	v_lshlrev_b32_e32 v174, 16, v233
	v_and_b32_e32 v175, 0xffff0000, v233
	v_lshlrev_b32_e32 v176, 16, v234
	v_and_b32_e32 v177, 0xffff0000, v234
	v_lshlrev_b32_e32 v178, 16, v235
	v_and_b32_e32 v179, 0xffff0000, v235
	v_pk_mul_f32 v[36:37], v[36:37], v[132:133] op_sel:[0,1] op_sel_hi:[1,1]
	v_pk_mul_f32 v[38:39], v[38:39], v[132:133] op_sel:[0,1] op_sel_hi:[1,1]
	v_pk_mul_f32 v[40:41], v[40:41], v[132:133] op_sel:[0,1] op_sel_hi:[1,1]
	v_pk_mul_f32 v[42:43], v[42:43], v[132:133] op_sel:[0,1] op_sel_hi:[1,1]
	v_pk_fma_f32 v[172:173], v[36:37], v[156:157], v[172:173]
	v_pk_fma_f32 v[174:175], v[38:39], v[158:159], v[174:175]
	v_pk_fma_f32 v[176:177], v[40:41], v[160:161], v[176:177]
	v_pk_fma_f32 v[178:179], v[42:43], v[162:163], v[178:179]
	v_fmac_f32_e32 v144, v172, v172
	v_fmac_f32_e32 v144, v173, v173
	v_fmac_f32_e32 v144, v174, v174
	v_fmac_f32_e32 v144, v175, v175
	v_fmac_f32_e32 v144, v176, v176
	v_fmac_f32_e32 v144, v177, v177
	v_fmac_f32_e32 v144, v178, v178
	v_fmac_f32_e32 v144, v179, v179
	v_cvt_pk_bf16_f32 v184, v172, v173
	v_cvt_pk_bf16_f32 v185, v174, v175
	v_cvt_pk_bf16_f32 v186, v176, v177
	v_cvt_pk_bf16_f32 v187, v178, v179
	global_store_dwordx4 v140, v[184:187], s[22:23] offset:256
	s_add_u32 s22, s60, 0x50000
	s_addc_u32 s23, s61, 0
	s_waitcnt vmcnt(14)
	v_lshlrev_b32_e32 v164, 16, v236
	v_and_b32_e32 v165, 0xffff0000, v236
	v_lshlrev_b32_e32 v166, 16, v237
	v_and_b32_e32 v167, 0xffff0000, v237
	v_lshlrev_b32_e32 v168, 16, v238
	v_and_b32_e32 v169, 0xffff0000, v238
	v_lshlrev_b32_e32 v170, 16, v239
	v_and_b32_e32 v171, 0xffff0000, v239
	v_pk_mul_f32 v[28:29], v[28:29], v[134:135] op_sel_hi:[1,0]
	v_pk_mul_f32 v[30:31], v[30:31], v[134:135] op_sel_hi:[1,0]
	v_pk_mul_f32 v[16:17], v[16:17], v[134:135] op_sel_hi:[1,0]
	v_pk_mul_f32 v[18:19], v[18:19], v[134:135] op_sel_hi:[1,0]
	v_pk_fma_f32 v[164:165], v[28:29], v[148:149], v[164:165]
	v_pk_fma_f32 v[166:167], v[30:31], v[150:151], v[166:167]
	v_pk_fma_f32 v[168:169], v[16:17], v[152:153], v[168:169]
	v_pk_fma_f32 v[170:171], v[18:19], v[154:155], v[170:171]
	v_mul_f32_e32 v145, v164, v164
	v_fmac_f32_e32 v145, v165, v165
	v_fmac_f32_e32 v145, v166, v166
	v_fmac_f32_e32 v145, v167, v167
	v_fmac_f32_e32 v145, v168, v168
	v_fmac_f32_e32 v145, v169, v169
	v_fmac_f32_e32 v145, v170, v170
	v_fmac_f32_e32 v145, v171, v171
	v_cvt_pk_bf16_f32 v180, v164, v165
	v_cvt_pk_bf16_f32 v181, v166, v167
	v_cvt_pk_bf16_f32 v182, v168, v169
	v_cvt_pk_bf16_f32 v183, v170, v171
	global_store_dwordx4 v140, v[180:183], s[22:23]
	v_lshlrev_b32_e32 v172, 16, v240
	v_and_b32_e32 v173, 0xffff0000, v240
	v_lshlrev_b32_e32 v174, 16, v241
	v_and_b32_e32 v175, 0xffff0000, v241
	v_lshlrev_b32_e32 v176, 16, v242
	v_and_b32_e32 v177, 0xffff0000, v242
	v_lshlrev_b32_e32 v178, 16, v243
	v_and_b32_e32 v179, 0xffff0000, v243
	v_pk_mul_f32 v[20:21], v[20:21], v[134:135] op_sel_hi:[1,0]
	v_pk_mul_f32 v[22:23], v[22:23], v[134:135] op_sel_hi:[1,0]
	v_pk_mul_f32 v[24:25], v[24:25], v[134:135] op_sel_hi:[1,0]
	v_pk_mul_f32 v[26:27], v[26:27], v[134:135] op_sel_hi:[1,0]
	v_pk_fma_f32 v[172:173], v[20:21], v[156:157], v[172:173]
	v_pk_fma_f32 v[174:175], v[22:23], v[158:159], v[174:175]
	v_pk_fma_f32 v[176:177], v[24:25], v[160:161], v[176:177]
	v_pk_fma_f32 v[178:179], v[26:27], v[162:163], v[178:179]
	v_fmac_f32_e32 v145, v172, v172
	v_fmac_f32_e32 v145, v173, v173
	v_fmac_f32_e32 v145, v174, v174
	v_fmac_f32_e32 v145, v175, v175
	v_fmac_f32_e32 v145, v176, v176
	v_fmac_f32_e32 v145, v177, v177
	v_fmac_f32_e32 v145, v178, v178
	v_fmac_f32_e32 v145, v179, v179
	v_cvt_pk_bf16_f32 v184, v172, v173
	v_cvt_pk_bf16_f32 v185, v174, v175
	v_cvt_pk_bf16_f32 v186, v176, v177
	v_cvt_pk_bf16_f32 v187, v178, v179
	global_store_dwordx4 v140, v[184:187], s[22:23] offset:256
	s_add_u32 s22, s60, 0x58000
	s_addc_u32 s23, s61, 0
	s_waitcnt vmcnt(14)
	v_lshlrev_b32_e32 v164, 16, v244
	v_and_b32_e32 v165, 0xffff0000, v244
	v_lshlrev_b32_e32 v166, 16, v245
	v_and_b32_e32 v167, 0xffff0000, v245
	v_lshlrev_b32_e32 v168, 16, v246
	v_and_b32_e32 v169, 0xffff0000, v246
	v_lshlrev_b32_e32 v170, 16, v247
	v_and_b32_e32 v171, 0xffff0000, v247
	v_pk_mul_f32 v[12:13], v[12:13], v[134:135] op_sel:[0,1] op_sel_hi:[1,1]
	v_pk_mul_f32 v[14:15], v[14:15], v[134:135] op_sel:[0,1] op_sel_hi:[1,1]
	v_pk_mul_f32 v[0:1], v[0:1], v[134:135] op_sel:[0,1] op_sel_hi:[1,1]
	v_pk_mul_f32 v[2:3], v[2:3], v[134:135] op_sel:[0,1] op_sel_hi:[1,1]
	v_pk_fma_f32 v[164:165], v[12:13], v[148:149], v[164:165]
	v_pk_fma_f32 v[166:167], v[14:15], v[150:151], v[166:167]
	v_pk_fma_f32 v[168:169], v[0:1], v[152:153], v[168:169]
	v_pk_fma_f32 v[170:171], v[2:3], v[154:155], v[170:171]
	v_mul_f32_e32 v146, v164, v164
	v_fmac_f32_e32 v146, v165, v165
	v_fmac_f32_e32 v146, v166, v166
	v_fmac_f32_e32 v146, v167, v167
	v_fmac_f32_e32 v146, v168, v168
	v_fmac_f32_e32 v146, v169, v169
	v_fmac_f32_e32 v146, v170, v170
	v_fmac_f32_e32 v146, v171, v171
	v_cvt_pk_bf16_f32 v180, v164, v165
	v_cvt_pk_bf16_f32 v181, v166, v167
	v_cvt_pk_bf16_f32 v182, v168, v169
	v_cvt_pk_bf16_f32 v183, v170, v171
	global_store_dwordx4 v140, v[180:183], s[22:23]
	v_lshlrev_b32_e32 v172, 16, v248
	v_and_b32_e32 v173, 0xffff0000, v248
	v_lshlrev_b32_e32 v174, 16, v249
	v_and_b32_e32 v175, 0xffff0000, v249
	v_lshlrev_b32_e32 v176, 16, v250
	v_and_b32_e32 v177, 0xffff0000, v250
	v_lshlrev_b32_e32 v178, 16, v251
	v_and_b32_e32 v179, 0xffff0000, v251
	v_pk_mul_f32 v[4:5], v[4:5], v[134:135] op_sel:[0,1] op_sel_hi:[1,1]
	v_pk_mul_f32 v[6:7], v[6:7], v[134:135] op_sel:[0,1] op_sel_hi:[1,1]
	v_pk_mul_f32 v[8:9], v[8:9], v[134:135] op_sel:[0,1] op_sel_hi:[1,1]
	v_pk_mul_f32 v[10:11], v[10:11], v[134:135] op_sel:[0,1] op_sel_hi:[1,1]
	v_pk_fma_f32 v[172:173], v[4:5], v[156:157], v[172:173]
	v_pk_fma_f32 v[174:175], v[6:7], v[158:159], v[174:175]
	v_pk_fma_f32 v[176:177], v[8:9], v[160:161], v[176:177]
	v_pk_fma_f32 v[178:179], v[10:11], v[162:163], v[178:179]
	v_fmac_f32_e32 v146, v172, v172
	v_fmac_f32_e32 v146, v173, v173
	v_fmac_f32_e32 v146, v174, v174
	v_fmac_f32_e32 v146, v175, v175
	v_fmac_f32_e32 v146, v176, v176
	v_fmac_f32_e32 v146, v177, v177
	v_fmac_f32_e32 v146, v178, v178
	v_fmac_f32_e32 v146, v179, v179
	v_cvt_pk_bf16_f32 v184, v172, v173
	v_cvt_pk_bf16_f32 v185, v174, v175
	v_cvt_pk_bf16_f32 v186, v176, v177
	v_cvt_pk_bf16_f32 v187, v178, v179
	global_store_dwordx4 v140, v[184:187], s[22:23] offset:256
	v_mov_b32_e32 v148, v138
	v_mov_b32_e32 v149, v139
	v_mov_b32_e32 v150, v141
	v_mov_b32_e32 v151, v142
	v_mov_b32_e32 v152, v143
	v_mov_b32_e32 v153, v144
	v_mov_b32_e32 v154, v145
	v_mov_b32_e32 v155, v146
	v_xor_b32_e32 v138, 16, v137
	v_xor_b32_e32 v139, 32, v137
	v_lshlrev_b32_e32 v138, 2, v138
	v_lshlrev_b32_e32 v139, 2, v139
	ds_bpermute_b32 v164, v138, v148
	ds_bpermute_b32 v165, v138, v149
	ds_bpermute_b32 v166, v138, v150
	ds_bpermute_b32 v167, v138, v151
	ds_bpermute_b32 v168, v138, v152
	ds_bpermute_b32 v169, v138, v153
	ds_bpermute_b32 v170, v138, v154
	ds_bpermute_b32 v171, v138, v155
	s_waitcnt lgkmcnt(0)
	v_add_f32_e32 v148, v148, v164
	v_add_f32_e32 v149, v149, v165
	v_add_f32_e32 v150, v150, v166
	v_add_f32_e32 v151, v151, v167
	v_add_f32_e32 v152, v152, v168
	v_add_f32_e32 v153, v153, v169
	v_add_f32_e32 v154, v154, v170
	v_add_f32_e32 v155, v155, v171
	ds_bpermute_b32 v164, v139, v148
	ds_bpermute_b32 v165, v139, v149
	ds_bpermute_b32 v166, v139, v150
	ds_bpermute_b32 v167, v139, v151
	ds_bpermute_b32 v168, v139, v152
	ds_bpermute_b32 v169, v139, v153
	ds_bpermute_b32 v170, v139, v154
	ds_bpermute_b32 v171, v139, v155
	s_waitcnt lgkmcnt(0)
	v_add_f32_e32 v148, v148, v164
	v_add_f32_e32 v149, v149, v165
	v_add_f32_e32 v150, v150, v166
	v_add_f32_e32 v151, v151, v167
	v_add_f32_e32 v152, v152, v168
	v_add_f32_e32 v153, v153, v169
	v_add_f32_e32 v154, v154, v170
	v_add_f32_e32 v155, v155, v171
	s_and_b32 s98, s2, 7
	s_lshl_b32 s98, s98, 3
	s_bfe_u32 s99, s2, 0x30003
	s_or_b32 s98, s98, s99
	s_lshr_b32 s99, s2, 6
	s_mul_i32 s99, s99, 0x42000
	s_lshl_b32 s98, s98, 10
	s_add_u32 s100, s56, s99
	s_addc_u32 s101, s57, 0
	s_add_u32 s100, s100, s98
	s_addc_u32 s101, s101, 0
	v_lshrrev_b32_e32 v158, 8, v136
	v_bfe_u32 v159, v136, 6, 2
	v_and_b32_e32 v160, 15, v136
	v_lshl_add_u32 v160, v158, 6, v160
	v_mul_u32_u24_e32 v159, 0x4200, v159
	v_add_u32_e32 v160, v160, v159
	v_lshlrev_b32_e32 v160, 2, v160
	v_bfe_u32 v161, v136, 4, 2
	v_cmp_eq_u32_e32 vcc, 0, v161
	s_and_saveexec_b64 s[0:1], vcc
	global_store_dword v160, v148, s[100:101]
	global_store_dword v160, v149, s[100:101] offset:64
	global_store_dword v160, v150, s[100:101] offset:128
	global_store_dword v160, v151, s[100:101] offset:192
	global_store_dword v160, v152, s[100:101] offset:512
	global_store_dword v160, v153, s[100:101] offset:576
	global_store_dword v160, v154, s[100:101] offset:640
	global_store_dword v160, v155, s[100:101] offset:704
	s_or_b64 exec, exec, s[0:1]
	v_bfe_u32 v183, v136, 1, 2
	v_lshrrev_b32_e32 v187, 6, v136
	v_lshlrev_b32_e32 v190, 11, v136
	v_lshrrev_b32_e32 v252, 1, v136
	v_and_b32_e32 v132, 48, v136
	v_and_b32_e32 v189, 63, v136
	v_lshrrev_b32_e32 v182, 3, v136
	v_lshlrev_b32_e32 v188, 2, v136
	v_lshl_add_u32 v186, v183, 6, 0
	v_and_b32_e32 v191, 15, v136
	s_cmpk_lt_i32 s2, 0x420
	v_mov_b32_e32 v0, v136
	s_cselect_b64 s[8:9], -1, 0
	s_cmpk_gt_i32 s2, 0x41f
	s_cbranch_scc1 .LBB0_863
	v_and_b32_e32 v4, 63, v0
	v_ashrrev_i32_e32 v0, 5, v0
	v_readlane_b32 s12, v253, 3
	v_and_b32_e32 v5, -2, v0
	v_lshlrev_b32_e32 v0, 4, v4
	v_mov_b32_e32 v1, 0
	v_readlane_b32 s13, v253, 4
	s_mov_b64 s[0:1], 0x1000
	v_readlane_b32 s14, v253, 5
	v_lshl_add_u64 v[2:3], s[12:13], 0, v[0:1]
	v_lshl_add_u64 v[16:17], v[2:3], 0, s[0:1]
	v_and_b32_e32 v2, 64, v137
	v_add_u32_e32 v2, 64, v2
	v_xor_b32_e32 v3, 32, v137
	v_cmp_lt_i32_e64 s[0:1], v3, v2
	v_readlane_b32 s15, v253, 6
	v_readlane_b32 s16, v253, 7
	v_cndmask_b32_e64 v3, v137, v3, s[0:1]
	v_lshlrev_b32_e32 v50, 2, v3
	v_xor_b32_e32 v3, 16, v137
	v_cmp_lt_i32_e64 s[0:1], v3, v2
	v_readlane_b32 s17, v253, 8
	v_readlane_b32 s18, v253, 9
	v_cndmask_b32_e64 v3, v137, v3, s[0:1]
	v_lshlrev_b32_e32 v51, 2, v3
	v_xor_b32_e32 v3, 8, v137
	v_cmp_lt_i32_e64 s[0:1], v3, v2
	v_readlane_b32 s19, v253, 10
	v_readlane_b32 s20, v253, 11
	v_cndmask_b32_e64 v3, v137, v3, s[0:1]
	v_lshlrev_b32_e32 v52, 2, v3
	v_xor_b32_e32 v3, 4, v137
	v_cmp_lt_i32_e64 s[0:1], v3, v2
	v_readlane_b32 s21, v253, 12
	v_readlane_b32 s22, v253, 13
	v_cndmask_b32_e64 v3, v137, v3, s[0:1]
	v_lshlrev_b32_e32 v53, 2, v3
	v_xor_b32_e32 v3, 2, v137
	v_cmp_lt_i32_e64 s[0:1], v3, v2
	v_readlane_b32 s23, v253, 14
	v_readlane_b32 s24, v253, 15
	v_cndmask_b32_e64 v3, v137, v3, s[0:1]
	v_readlane_b32 s25, v253, 16
	v_readlane_b32 s26, v253, 17
	v_readlane_b32 s27, v253, 18
	v_mul_u32_u24_e32 v0, 0x4200, v4
	v_lshlrev_b32_e32 v54, 2, v3
	v_xor_b32_e32 v3, 1, v137
	v_cmp_lt_i32_e64 s[0:1], v3, v2
	v_lshlrev_b32_e32 v0, 2, v0
	v_readlane_b32 s12, v253, 51
	v_cndmask_b32_e64 v2, v137, v3, s[0:1]
	v_lshl_add_u64 v[18:19], s[44:45], 0, v[0:1]
	v_lshlrev_b32_e32 v0, 3, v4
	v_readlane_b32 s13, v253, 52
	v_readlane_b32 s14, v253, 53
	v_readlane_b32 s15, v253, 54
	v_cmp_gt_u32_e32 vcc, 16, v4
	v_lshlrev_b32_e32 v55, 2, v2
	v_cmp_eq_u32_e64 s[0:1], 0, v4
	v_lshl_add_u64 v[20:21], s[60:61], 0, v[0:1]
	v_lshl_add_u64 v[22:23], s[14:15], 0, v[0:1]
	v_lshl_add_u64 v[24:25], s[58:59], 0, v[0:1]
	v_lshl_add_u32 v26, s2, 4, v5
	s_lshl_b32 s3, s38, 4
	v_mov_b32_e32 v56, 0x358637bd
	s_mov_b32 s12, 0x800000
	s_mov_b32 s13, s2
	v_readlane_b32 s16, v253, 55
	v_readlane_b32 s17, v253, 56
	v_readlane_b32 s18, v253, 57
	v_readlane_b32 s19, v253, 58
	v_readlane_b32 s20, v253, 59
	v_readlane_b32 s21, v253, 60
	v_readlane_b32 s22, v253, 61
	v_readlane_b32 s23, v253, 62
	v_readlane_b32 s24, v253, 63
	v_readlane_b32 s25, v254, 0
	v_readlane_b32 s26, v254, 1
	v_readlane_b32 s27, v254, 2
	s_addk_i32 s13, 0x400
	v_add_u32_e32 v26, 0x4000, v26
	s_cmpk_lt_i32 s13, 0x420
	s_cbranch_scc0 .LBB0_863
	s_branch .LBB0_855

.LBB0_1243:
	s_or_b64 exec, exec, s[0:1]
	s_waitcnt lgkmcnt(0)
	s_barrier
	s_and_b32 s98, s2, 7
	s_lshl_b32 s98, s98, 3
	s_bfe_u32 s99, s2, 0x30003
	s_or_b32 s98, s98, s99
	s_lshr_b32 s99, s2, 6
	v_and_b32_e32 v172, 0xff, v136
	v_lshrrev_b32_e32 v173, 8, v136
	v_mul_u32_u24_e32 v173, 0x84000, v173
	v_lshl_add_u32 v172, v172, 2, v173
	s_lshl_b32 s24, s98, 10
	s_add_u32 s18, s44, s24
	s_addc_u32 s19, s45, 0
	global_load_dword v164, v172, s[18:19]
	s_add_u32 s18, s18, 0x10800
	s_addc_u32 s19, s19, 0
	global_load_dword v165, v172, s[18:19]
	s_add_u32 s18, s18, 0x10800
	s_addc_u32 s19, s19, 0
	global_load_dword v166, v172, s[18:19]
	s_add_u32 s18, s18, 0x10800
	s_addc_u32 s19, s19, 0
	global_load_dword v167, v172, s[18:19]
	s_add_u32 s18, s18, 0x10800
	s_addc_u32 s19, s19, 0
	global_load_dword v168, v172, s[18:19]
	s_add_u32 s18, s18, 0x10800
	s_addc_u32 s19, s19, 0
	global_load_dword v169, v172, s[18:19]
	s_add_u32 s18, s18, 0x10800
	s_addc_u32 s19, s19, 0
	global_load_dword v170, v172, s[18:19]
	s_add_u32 s18, s18, 0x10800
	s_addc_u32 s19, s19, 0
	global_load_dword v171, v172, s[18:19]
	v_lshrrev_b32_e32 v141, 8, v136
	v_and_b32_e32 v142, 15, v136
	v_lshl_add_u32 v141, v141, 6, v142
	v_bfe_u32 v144, v136, 6, 2
	v_bfe_u32 v145, v136, 4, 2
	v_lshlrev_b32_e32 v144, 5, v144
	v_lshl_add_u32 v144, v145, 3, v144
	s_lshl_b32 s24, s99, 8
	v_add_u32_e32 v144, s24, v144
	s_lshl_b32 s25, s98, 8
	v_add_u32_e32 v145, s25, v141
	v_lshl_add_u32 v146, v145, 10, v144
	v_lshlrev_b32_e32 v140, 1, v146
	v_lshlrev_b32_e32 v147, 2, v144
	v_readlane_b32 s18, v253, 3
	v_readlane_b32 s19, v253, 4
	s_mov_b32 s20, s60
	s_mov_b32 s21, s61
	s_nop 4
	s_add_u32 s18, s18, 0x3000
	s_addc_u32 s19, s19, 0
	global_load_dwordx4 v[148:151], v147, s[18:19]
	global_load_dwordx4 v[152:155], v147, s[18:19] offset:16
	global_load_dwordx4 v[156:159], v147, s[18:19] offset:512
	global_load_dwordx4 v[160:163], v147, s[18:19] offset:528
	s_add_u32 s22, s20, 0x0
	s_addc_u32 s23, s21, 0
	global_load_dwordx4 v[188:191], v140, s[22:23] nt
	global_load_dwordx4 v[192:195], v140, s[22:23] offset:256 nt
	s_add_u32 s22, s20, 0x8000
	s_addc_u32 s23, s21, 0
	global_load_dwordx4 v[196:199], v140, s[22:23] nt
	global_load_dwordx4 v[200:203], v140, s[22:23] offset:256 nt
	s_add_u32 s22, s20, 0x10000
	s_addc_u32 s23, s21, 0
	global_load_dwordx4 v[204:207], v140, s[22:23] nt
	global_load_dwordx4 v[208:211], v140, s[22:23] offset:256 nt
	s_add_u32 s22, s20, 0x18000
	s_addc_u32 s23, s21, 0
	global_load_dwordx4 v[212:215], v140, s[22:23] nt
	global_load_dwordx4 v[216:219], v140, s[22:23] offset:256 nt
	s_add_u32 s22, s20, 0x40000
	s_addc_u32 s23, s21, 0
	global_load_dwordx4 v[220:223], v140, s[22:23] nt
	global_load_dwordx4 v[224:227], v140, s[22:23] offset:256 nt
	s_add_u32 s22, s20, 0x48000
	s_addc_u32 s23, s21, 0
	global_load_dwordx4 v[228:231], v140, s[22:23] nt
	global_load_dwordx4 v[232:235], v140, s[22:23] offset:256 nt
	s_add_u32 s22, s20, 0x50000
	s_addc_u32 s23, s21, 0
	global_load_dwordx4 v[236:239], v140, s[22:23] nt
	global_load_dwordx4 v[240:243], v140, s[22:23] offset:256 nt
	s_add_u32 s22, s20, 0x58000
	s_addc_u32 s23, s21, 0
	global_load_dwordx4 v[244:247], v140, s[22:23] nt
	global_load_dwordx4 v[248:251], v140, s[22:23] offset:256 nt
	s_waitcnt vmcnt(20)
	v_add_f32_e32 v164, v164, v165
	v_add_f32_e32 v164, v164, v166
	v_add_f32_e32 v164, v164, v167
	v_add_f32_e32 v164, v164, v168
	v_add_f32_e32 v164, v164, v169
	v_add_f32_e32 v164, v164, v170
	v_add_f32_e32 v164, v164, v171
	v_lshlrev_b32_e32 v173, 2, v136
	ds_write_b32 v173, v164
	s_waitcnt lgkmcnt(0)
	s_barrier
	v_lshlrev_b32_e32 v142, 2, v141
	ds_read_b32 v128, v142 offset:0
	ds_read_b32 v174, v142 offset:1024
	ds_read_b32 v129, v142 offset:64
	ds_read_b32 v175, v142 offset:1088
	ds_read_b32 v130, v142 offset:128
	ds_read_b32 v176, v142 offset:1152
	ds_read_b32 v131, v142 offset:192
	ds_read_b32 v177, v142 offset:1216
	ds_read_b32 v132, v142 offset:512
	ds_read_b32 v178, v142 offset:1536
	ds_read_b32 v133, v142 offset:576
	ds_read_b32 v179, v142 offset:1600
	ds_read_b32 v134, v142 offset:640
	ds_read_b32 v180, v142 offset:1664
	ds_read_b32 v135, v142 offset:704
	ds_read_b32 v181, v142 offset:1728
	s_waitcnt lgkmcnt(0)
	s_mov_b32 s101, 0x3a800000
	v_mov_b32_e32 v143, 0x358637bd
	v_add_f32_e32 v128, v128, v174
	v_add_f32_e32 v129, v129, v175
	v_add_f32_e32 v130, v130, v176
	v_add_f32_e32 v131, v131, v177
	v_add_f32_e32 v132, v132, v178
	v_add_f32_e32 v133, v133, v179
	v_add_f32_e32 v134, v134, v180
	v_add_f32_e32 v135, v135, v181
	v_fma_f32 v128, v128, s101, v143
	v_fma_f32 v129, v129, s101, v143
	v_fma_f32 v130, v130, s101, v143
	v_fma_f32 v131, v131, s101, v143
	v_fma_f32 v132, v132, s101, v143
	v_fma_f32 v133, v133, s101, v143
	v_fma_f32 v134, v134, s101, v143
	v_fma_f32 v135, v135, s101, v143
	v_rsq_f32_e32 v128, v128
	v_rsq_f32_e32 v129, v129
	v_rsq_f32_e32 v130, v130
	v_rsq_f32_e32 v131, v131
	v_rsq_f32_e32 v132, v132
	v_rsq_f32_e32 v133, v133
	v_rsq_f32_e32 v134, v134
	v_rsq_f32_e32 v135, v135
	s_add_u32 s22, s64, 0x0
	s_addc_u32 s23, s65, 0
	s_waitcnt vmcnt(14)
	v_lshlrev_b32_e32 v164, 16, v188
	v_and_b32_e32 v165, 0xffff0000, v188
	v_lshlrev_b32_e32 v166, 16, v189
	v_and_b32_e32 v167, 0xffff0000, v189
	v_lshlrev_b32_e32 v168, 16, v190
	v_and_b32_e32 v169, 0xffff0000, v190
	v_lshlrev_b32_e32 v170, 16, v191
	v_and_b32_e32 v171, 0xffff0000, v191
	v_pk_mul_f32 v[124:125], v[124:125], v[128:129] op_sel_hi:[1,0]
	v_pk_mul_f32 v[126:127], v[126:127], v[128:129] op_sel_hi:[1,0]
	v_pk_mul_f32 v[112:113], v[112:113], v[128:129] op_sel_hi:[1,0]
	v_pk_mul_f32 v[114:115], v[114:115], v[128:129] op_sel_hi:[1,0]
	v_pk_fma_f32 v[164:165], v[124:125], v[148:149], v[164:165]
	v_pk_fma_f32 v[166:167], v[126:127], v[150:151], v[166:167]
	v_pk_fma_f32 v[168:169], v[112:113], v[152:153], v[168:169]
	v_pk_fma_f32 v[170:171], v[114:115], v[154:155], v[170:171]
	v_mul_f32_e32 v138, v164, v164
	v_fmac_f32_e32 v138, v165, v165
	v_fmac_f32_e32 v138, v166, v166
	v_fmac_f32_e32 v138, v167, v167
	v_fmac_f32_e32 v138, v168, v168
	v_fmac_f32_e32 v138, v169, v169
	v_fmac_f32_e32 v138, v170, v170
	v_fmac_f32_e32 v138, v171, v171
	v_cvt_pk_bf16_f32 v180, v164, v165
	v_cvt_pk_bf16_f32 v181, v166, v167
	v_cvt_pk_bf16_f32 v182, v168, v169
	v_cvt_pk_bf16_f32 v183, v170, v171
	global_store_dwordx4 v140, v[180:183], s[22:23]
	v_lshlrev_b32_e32 v172, 16, v192
	v_and_b32_e32 v173, 0xffff0000, v192
	v_lshlrev_b32_e32 v174, 16, v193
	v_and_b32_e32 v175, 0xffff0000, v193
	v_lshlrev_b32_e32 v176, 16, v194
	v_and_b32_e32 v177, 0xffff0000, v194
	v_lshlrev_b32_e32 v178, 16, v195
	v_and_b32_e32 v179, 0xffff0000, v195
	v_pk_mul_f32 v[120:121], v[120:121], v[128:129] op_sel_hi:[1,0]
	v_pk_mul_f32 v[122:123], v[122:123], v[128:129] op_sel_hi:[1,0]
	v_pk_mul_f32 v[116:117], v[116:117], v[128:129] op_sel_hi:[1,0]
	v_pk_mul_f32 v[118:119], v[118:119], v[128:129] op_sel_hi:[1,0]
	v_pk_fma_f32 v[172:173], v[120:121], v[156:157], v[172:173]
	v_pk_fma_f32 v[174:175], v[122:123], v[158:159], v[174:175]
	v_pk_fma_f32 v[176:177], v[116:117], v[160:161], v[176:177]
	v_pk_fma_f32 v[178:179], v[118:119], v[162:163], v[178:179]
	v_fmac_f32_e32 v138, v172, v172
	v_fmac_f32_e32 v138, v173, v173
	v_fmac_f32_e32 v138, v174, v174
	v_fmac_f32_e32 v138, v175, v175
	v_fmac_f32_e32 v138, v176, v176
	v_fmac_f32_e32 v138, v177, v177
	v_fmac_f32_e32 v138, v178, v178
	v_fmac_f32_e32 v138, v179, v179
	v_cvt_pk_bf16_f32 v184, v172, v173
	v_cvt_pk_bf16_f32 v185, v174, v175
	v_cvt_pk_bf16_f32 v186, v176, v177
	v_cvt_pk_bf16_f32 v187, v178, v179
	global_store_dwordx4 v140, v[184:187], s[22:23] offset:256
	s_add_u32 s22, s64, 0x8000
	s_addc_u32 s23, s65, 0
	s_waitcnt vmcnt(14)
	v_lshlrev_b32_e32 v164, 16, v196
	v_and_b32_e32 v165, 0xffff0000, v196
	v_lshlrev_b32_e32 v166, 16, v197
	v_and_b32_e32 v167, 0xffff0000, v197
	v_lshlrev_b32_e32 v168, 16, v198
	v_and_b32_e32 v169, 0xffff0000, v198
	v_lshlrev_b32_e32 v170, 16, v199
	v_and_b32_e32 v171, 0xffff0000, v199
	v_pk_mul_f32 v[108:109], v[108:109], v[128:129] op_sel:[0,1] op_sel_hi:[1,1]
	v_pk_mul_f32 v[110:111], v[110:111], v[128:129] op_sel:[0,1] op_sel_hi:[1,1]
	v_pk_mul_f32 v[96:97], v[96:97], v[128:129] op_sel:[0,1] op_sel_hi:[1,1]
	v_pk_mul_f32 v[98:99], v[98:99], v[128:129] op_sel:[0,1] op_sel_hi:[1,1]
	v_pk_fma_f32 v[164:165], v[108:109], v[148:149], v[164:165]
	v_pk_fma_f32 v[166:167], v[110:111], v[150:151], v[166:167]
	v_pk_fma_f32 v[168:169], v[96:97], v[152:153], v[168:169]
	v_pk_fma_f32 v[170:171], v[98:99], v[154:155], v[170:171]
	v_mul_f32_e32 v139, v164, v164
	v_fmac_f32_e32 v139, v165, v165
	v_fmac_f32_e32 v139, v166, v166
	v_fmac_f32_e32 v139, v167, v167
	v_fmac_f32_e32 v139, v168, v168
	v_fmac_f32_e32 v139, v169, v169
	v_fmac_f32_e32 v139, v170, v170
	v_fmac_f32_e32 v139, v171, v171
	v_cvt_pk_bf16_f32 v180, v164, v165
	v_cvt_pk_bf16_f32 v181, v166, v167
	v_cvt_pk_bf16_f32 v182, v168, v169
	v_cvt_pk_bf16_f32 v183, v170, v171
	global_store_dwordx4 v140, v[180:183], s[22:23]
	v_lshlrev_b32_e32 v172, 16, v200
	v_and_b32_e32 v173, 0xffff0000, v200
	v_lshlrev_b32_e32 v174, 16, v201
	v_and_b32_e32 v175, 0xffff0000, v201
	v_lshlrev_b32_e32 v176, 16, v202
	v_and_b32_e32 v177, 0xffff0000, v202
	v_lshlrev_b32_e32 v178, 16, v203
	v_and_b32_e32 v179, 0xffff0000, v203
	v_pk_mul_f32 v[100:101], v[100:101], v[128:129] op_sel:[0,1] op_sel_hi:[1,1]
	v_pk_mul_f32 v[102:103], v[102:103], v[128:129] op_sel:[0,1] op_sel_hi:[1,1]
	v_pk_mul_f32 v[104:105], v[104:105], v[128:129] op_sel:[0,1] op_sel_hi:[1,1]
	v_pk_mul_f32 v[106:107], v[106:107], v[128:129] op_sel:[0,1] op_sel_hi:[1,1]
	v_pk_fma_f32 v[172:173], v[100:101], v[156:157], v[172:173]
	v_pk_fma_f32 v[174:175], v[102:103], v[158:159], v[174:175]
	v_pk_fma_f32 v[176:177], v[104:105], v[160:161], v[176:177]
	v_pk_fma_f32 v[178:179], v[106:107], v[162:163], v[178:179]
	v_fmac_f32_e32 v139, v172, v172
	v_fmac_f32_e32 v139, v173, v173
	v_fmac_f32_e32 v139, v174, v174
	v_fmac_f32_e32 v139, v175, v175
	v_fmac_f32_e32 v139, v176, v176
	v_fmac_f32_e32 v139, v177, v177
	v_fmac_f32_e32 v139, v178, v178
	v_fmac_f32_e32 v139, v179, v179
	v_cvt_pk_bf16_f32 v184, v172, v173
	v_cvt_pk_bf16_f32 v185, v174, v175
	v_cvt_pk_bf16_f32 v186, v176, v177
	v_cvt_pk_bf16_f32 v187, v178, v179
	global_store_dwordx4 v140, v[184:187], s[22:23] offset:256
	s_add_u32 s22, s64, 0x10000
	s_addc_u32 s23, s65, 0
	s_waitcnt vmcnt(14)
	v_lshlrev_b32_e32 v164, 16, v204
	v_and_b32_e32 v165, 0xffff0000, v204
	v_lshlrev_b32_e32 v166, 16, v205
	v_and_b32_e32 v167, 0xffff0000, v205
	v_lshlrev_b32_e32 v168, 16, v206
	v_and_b32_e32 v169, 0xffff0000, v206
	v_lshlrev_b32_e32 v170, 16, v207
	v_and_b32_e32 v171, 0xffff0000, v207
	v_pk_mul_f32 v[92:93], v[92:93], v[130:131] op_sel_hi:[1,0]
	v_pk_mul_f32 v[94:95], v[94:95], v[130:131] op_sel_hi:[1,0]
	v_pk_mul_f32 v[80:81], v[80:81], v[130:131] op_sel_hi:[1,0]
	v_pk_mul_f32 v[82:83], v[82:83], v[130:131] op_sel_hi:[1,0]
	v_pk_fma_f32 v[164:165], v[92:93], v[148:149], v[164:165]
	v_pk_fma_f32 v[166:167], v[94:95], v[150:151], v[166:167]
	v_pk_fma_f32 v[168:169], v[80:81], v[152:153], v[168:169]
	v_pk_fma_f32 v[170:171], v[82:83], v[154:155], v[170:171]
	v_mul_f32_e32 v141, v164, v164
	v_fmac_f32_e32 v141, v165, v165
	v_fmac_f32_e32 v141, v166, v166
	v_fmac_f32_e32 v141, v167, v167
	v_fmac_f32_e32 v141, v168, v168
	v_fmac_f32_e32 v141, v169, v169
	v_fmac_f32_e32 v141, v170, v170
	v_fmac_f32_e32 v141, v171, v171
	v_cvt_pk_bf16_f32 v180, v164, v165
	v_cvt_pk_bf16_f32 v181, v166, v167
	v_cvt_pk_bf16_f32 v182, v168, v169
	v_cvt_pk_bf16_f32 v183, v170, v171
	global_store_dwordx4 v140, v[180:183], s[22:23]
	v_lshlrev_b32_e32 v172, 16, v208
	v_and_b32_e32 v173, 0xffff0000, v208
	v_lshlrev_b32_e32 v174, 16, v209
	v_and_b32_e32 v175, 0xffff0000, v209
	v_lshlrev_b32_e32 v176, 16, v210
	v_and_b32_e32 v177, 0xffff0000, v210
	v_lshlrev_b32_e32 v178, 16, v211
	v_and_b32_e32 v179, 0xffff0000, v211
	v_pk_mul_f32 v[84:85], v[84:85], v[130:131] op_sel_hi:[1,0]
	v_pk_mul_f32 v[86:87], v[86:87], v[130:131] op_sel_hi:[1,0]
	v_pk_mul_f32 v[88:89], v[88:89], v[130:131] op_sel_hi:[1,0]
	v_pk_mul_f32 v[90:91], v[90:91], v[130:131] op_sel_hi:[1,0]
	v_pk_fma_f32 v[172:173], v[84:85], v[156:157], v[172:173]
	v_pk_fma_f32 v[174:175], v[86:87], v[158:159], v[174:175]
	v_pk_fma_f32 v[176:177], v[88:89], v[160:161], v[176:177]
	v_pk_fma_f32 v[178:179], v[90:91], v[162:163], v[178:179]
	v_fmac_f32_e32 v141, v172, v172
	v_fmac_f32_e32 v141, v173, v173
	v_fmac_f32_e32 v141, v174, v174
	v_fmac_f32_e32 v141, v175, v175
	v_fmac_f32_e32 v141, v176, v176
	v_fmac_f32_e32 v141, v177, v177
	v_fmac_f32_e32 v141, v178, v178
	v_fmac_f32_e32 v141, v179, v179
	v_cvt_pk_bf16_f32 v184, v172, v173
	v_cvt_pk_bf16_f32 v185, v174, v175
	v_cvt_pk_bf16_f32 v186, v176, v177
	v_cvt_pk_bf16_f32 v187, v178, v179
	global_store_dwordx4 v140, v[184:187], s[22:23] offset:256
	s_add_u32 s22, s64, 0x18000
	s_addc_u32 s23, s65, 0
	s_waitcnt vmcnt(14)
	v_lshlrev_b32_e32 v164, 16, v212
	v_and_b32_e32 v165, 0xffff0000, v212
	v_lshlrev_b32_e32 v166, 16, v213
	v_and_b32_e32 v167, 0xffff0000, v213
	v_lshlrev_b32_e32 v168, 16, v214
	v_and_b32_e32 v169, 0xffff0000, v214
	v_lshlrev_b32_e32 v170, 16, v215
	v_and_b32_e32 v171, 0xffff0000, v215
	v_pk_mul_f32 v[76:77], v[76:77], v[130:131] op_sel:[0,1] op_sel_hi:[1,1]
	v_pk_mul_f32 v[78:79], v[78:79], v[130:131] op_sel:[0,1] op_sel_hi:[1,1]
	v_pk_mul_f32 v[64:65], v[64:65], v[130:131] op_sel:[0,1] op_sel_hi:[1,1]
	v_pk_mul_f32 v[66:67], v[66:67], v[130:131] op_sel:[0,1] op_sel_hi:[1,1]
	v_pk_fma_f32 v[164:165], v[76:77], v[148:149], v[164:165]
	v_pk_fma_f32 v[166:167], v[78:79], v[150:151], v[166:167]
	v_pk_fma_f32 v[168:169], v[64:65], v[152:153], v[168:169]
	v_pk_fma_f32 v[170:171], v[66:67], v[154:155], v[170:171]
	v_mul_f32_e32 v142, v164, v164
	v_fmac_f32_e32 v142, v165, v165
	v_fmac_f32_e32 v142, v166, v166
	v_fmac_f32_e32 v142, v167, v167
	v_fmac_f32_e32 v142, v168, v168
	v_fmac_f32_e32 v142, v169, v169
	v_fmac_f32_e32 v142, v170, v170
	v_fmac_f32_e32 v142, v171, v171
	v_cvt_pk_bf16_f32 v180, v164, v165
	v_cvt_pk_bf16_f32 v181, v166, v167
	v_cvt_pk_bf16_f32 v182, v168, v169
	v_cvt_pk_bf16_f32 v183, v170, v171
	global_store_dwordx4 v140, v[180:183], s[22:23]
	v_lshlrev_b32_e32 v172, 16, v216
	v_and_b32_e32 v173, 0xffff0000, v216
	v_lshlrev_b32_e32 v174, 16, v217
	v_and_b32_e32 v175, 0xffff0000, v217
	v_lshlrev_b32_e32 v176, 16, v218
	v_and_b32_e32 v177, 0xffff0000, v218
	v_lshlrev_b32_e32 v178, 16, v219
	v_and_b32_e32 v179, 0xffff0000, v219
	v_pk_mul_f32 v[68:69], v[68:69], v[130:131] op_sel:[0,1] op_sel_hi:[1,1]
	v_pk_mul_f32 v[70:71], v[70:71], v[130:131] op_sel:[0,1] op_sel_hi:[1,1]
	v_pk_mul_f32 v[72:73], v[72:73], v[130:131] op_sel:[0,1] op_sel_hi:[1,1]
	v_pk_mul_f32 v[74:75], v[74:75], v[130:131] op_sel:[0,1] op_sel_hi:[1,1]
	v_pk_fma_f32 v[172:173], v[68:69], v[156:157], v[172:173]
	v_pk_fma_f32 v[174:175], v[70:71], v[158:159], v[174:175]
	v_pk_fma_f32 v[176:177], v[72:73], v[160:161], v[176:177]
	v_pk_fma_f32 v[178:179], v[74:75], v[162:163], v[178:179]
	v_fmac_f32_e32 v142, v172, v172
	v_fmac_f32_e32 v142, v173, v173
	v_fmac_f32_e32 v142, v174, v174
	v_fmac_f32_e32 v142, v175, v175
	v_fmac_f32_e32 v142, v176, v176
	v_fmac_f32_e32 v142, v177, v177
	v_fmac_f32_e32 v142, v178, v178
	v_fmac_f32_e32 v142, v179, v179
	v_cvt_pk_bf16_f32 v184, v172, v173
	v_cvt_pk_bf16_f32 v185, v174, v175
	v_cvt_pk_bf16_f32 v186, v176, v177
	v_cvt_pk_bf16_f32 v187, v178, v179
	global_store_dwordx4 v140, v[184:187], s[22:23] offset:256
	s_add_u32 s22, s64, 0x40000
	s_addc_u32 s23, s65, 0
	s_waitcnt vmcnt(14)
	v_lshlrev_b32_e32 v164, 16, v220
	v_and_b32_e32 v165, 0xffff0000, v220
	v_lshlrev_b32_e32 v166, 16, v221
	v_and_b32_e32 v167, 0xffff0000, v221
	v_lshlrev_b32_e32 v168, 16, v222
	v_and_b32_e32 v169, 0xffff0000, v222
	v_lshlrev_b32_e32 v170, 16, v223
	v_and_b32_e32 v171, 0xffff0000, v223
	v_pk_mul_f32 v[60:61], v[60:61], v[132:133] op_sel_hi:[1,0]
	v_pk_mul_f32 v[62:63], v[62:63], v[132:133] op_sel_hi:[1,0]
	v_pk_mul_f32 v[48:49], v[48:49], v[132:133] op_sel_hi:[1,0]
	v_pk_mul_f32 v[50:51], v[50:51], v[132:133] op_sel_hi:[1,0]
	v_pk_fma_f32 v[164:165], v[60:61], v[148:149], v[164:165]
	v_pk_fma_f32 v[166:167], v[62:63], v[150:151], v[166:167]
	v_pk_fma_f32 v[168:169], v[48:49], v[152:153], v[168:169]
	v_pk_fma_f32 v[170:171], v[50:51], v[154:155], v[170:171]
	v_mul_f32_e32 v143, v164, v164
	v_fmac_f32_e32 v143, v165, v165
	v_fmac_f32_e32 v143, v166, v166
	v_fmac_f32_e32 v143, v167, v167
	v_fmac_f32_e32 v143, v168, v168
	v_fmac_f32_e32 v143, v169, v169
	v_fmac_f32_e32 v143, v170, v170
	v_fmac_f32_e32 v143, v171, v171
	v_cvt_pk_bf16_f32 v180, v164, v165
	v_cvt_pk_bf16_f32 v181, v166, v167
	v_cvt_pk_bf16_f32 v182, v168, v169
	v_cvt_pk_bf16_f32 v183, v170, v171
	global_store_dwordx4 v140, v[180:183], s[22:23]
	v_lshlrev_b32_e32 v172, 16, v224
	v_and_b32_e32 v173, 0xffff0000, v224
	v_lshlrev_b32_e32 v174, 16, v225
	v_and_b32_e32 v175, 0xffff0000, v225
	v_lshlrev_b32_e32 v176, 16, v226
	v_and_b32_e32 v177, 0xffff0000, v226
	v_lshlrev_b32_e32 v178, 16, v227
	v_and_b32_e32 v179, 0xffff0000, v227
	v_pk_mul_f32 v[52:53], v[52:53], v[132:133] op_sel_hi:[1,0]
	v_pk_mul_f32 v[54:55], v[54:55], v[132:133] op_sel_hi:[1,0]
	v_pk_mul_f32 v[56:57], v[56:57], v[132:133] op_sel_hi:[1,0]
	v_pk_mul_f32 v[58:59], v[58:59], v[132:133] op_sel_hi:[1,0]
	v_pk_fma_f32 v[172:173], v[52:53], v[156:157], v[172:173]
	v_pk_fma_f32 v[174:175], v[54:55], v[158:159], v[174:175]
	v_pk_fma_f32 v[176:177], v[56:57], v[160:161], v[176:177]
	v_pk_fma_f32 v[178:179], v[58:59], v[162:163], v[178:179]
	v_fmac_f32_e32 v143, v172, v172
	v_fmac_f32_e32 v143, v173, v173
	v_fmac_f32_e32 v143, v174, v174
	v_fmac_f32_e32 v143, v175, v175
	v_fmac_f32_e32 v143, v176, v176
	v_fmac_f32_e32 v143, v177, v177
	v_fmac_f32_e32 v143, v178, v178
	v_fmac_f32_e32 v143, v179, v179
	v_cvt_pk_bf16_f32 v184, v172, v173
	v_cvt_pk_bf16_f32 v185, v174, v175
	v_cvt_pk_bf16_f32 v186, v176, v177
	v_cvt_pk_bf16_f32 v187, v178, v179
	global_store_dwordx4 v140, v[184:187], s[22:23] offset:256
	s_add_u32 s22, s64, 0x48000
	s_addc_u32 s23, s65, 0
	s_waitcnt vmcnt(14)
	v_lshlrev_b32_e32 v164, 16, v228
	v_and_b32_e32 v165, 0xffff0000, v228
	v_lshlrev_b32_e32 v166, 16, v229
	v_and_b32_e32 v167, 0xffff0000, v229
	v_lshlrev_b32_e32 v168, 16, v230
	v_and_b32_e32 v169, 0xffff0000, v230
	v_lshlrev_b32_e32 v170, 16, v231
	v_and_b32_e32 v171, 0xffff0000, v231
	v_pk_mul_f32 v[44:45], v[44:45], v[132:133] op_sel:[0,1] op_sel_hi:[1,1]
	v_pk_mul_f32 v[46:47], v[46:47], v[132:133] op_sel:[0,1] op_sel_hi:[1,1]
	v_pk_mul_f32 v[32:33], v[32:33], v[132:133] op_sel:[0,1] op_sel_hi:[1,1]
	v_pk_mul_f32 v[34:35], v[34:35], v[132:133] op_sel:[0,1] op_sel_hi:[1,1]
	v_pk_fma_f32 v[164:165], v[44:45], v[148:149], v[164:165]
	v_pk_fma_f32 v[166:167], v[46:47], v[150:151], v[166:167]
	v_pk_fma_f32 v[168:169], v[32:33], v[152:153], v[168:169]
	v_pk_fma_f32 v[170:171], v[34:35], v[154:155], v[170:171]
	v_mul_f32_e32 v144, v164, v164
	v_fmac_f32_e32 v144, v165, v165
	v_fmac_f32_e32 v144, v166, v166
	v_fmac_f32_e32 v144, v167, v167
	v_fmac_f32_e32 v144, v168, v168
	v_fmac_f32_e32 v144, v169, v169
	v_fmac_f32_e32 v144, v170, v170
	v_fmac_f32_e32 v144, v171, v171
	v_cvt_pk_bf16_f32 v180, v164, v165
	v_cvt_pk_bf16_f32 v181, v166, v167
	v_cvt_pk_bf16_f32 v182, v168, v169
	v_cvt_pk_bf16_f32 v183, v170, v171
	global_store_dwordx4 v140, v[180:183], s[22:23]
	v_lshlrev_b32_e32 v172, 16, v232
	v_and_b32_e32 v173, 0xffff0000, v232
	v_lshlrev_b32_e32 v174, 16, v233
	v_and_b32_e32 v175, 0xffff0000, v233
	v_lshlrev_b32_e32 v176, 16, v234
	v_and_b32_e32 v177, 0xffff0000, v234
	v_lshlrev_b32_e32 v178, 16, v235
	v_and_b32_e32 v179, 0xffff0000, v235
	v_pk_mul_f32 v[36:37], v[36:37], v[132:133] op_sel:[0,1] op_sel_hi:[1,1]
	v_pk_mul_f32 v[38:39], v[38:39], v[132:133] op_sel:[0,1] op_sel_hi:[1,1]
	v_pk_mul_f32 v[40:41], v[40:41], v[132:133] op_sel:[0,1] op_sel_hi:[1,1]
	v_pk_mul_f32 v[42:43], v[42:43], v[132:133] op_sel:[0,1] op_sel_hi:[1,1]
	v_pk_fma_f32 v[172:173], v[36:37], v[156:157], v[172:173]
	v_pk_fma_f32 v[174:175], v[38:39], v[158:159], v[174:175]
	v_pk_fma_f32 v[176:177], v[40:41], v[160:161], v[176:177]
	v_pk_fma_f32 v[178:179], v[42:43], v[162:163], v[178:179]
	v_fmac_f32_e32 v144, v172, v172
	v_fmac_f32_e32 v144, v173, v173
	v_fmac_f32_e32 v144, v174, v174
	v_fmac_f32_e32 v144, v175, v175
	v_fmac_f32_e32 v144, v176, v176
	v_fmac_f32_e32 v144, v177, v177
	v_fmac_f32_e32 v144, v178, v178
	v_fmac_f32_e32 v144, v179, v179
	v_cvt_pk_bf16_f32 v184, v172, v173
	v_cvt_pk_bf16_f32 v185, v174, v175
	v_cvt_pk_bf16_f32 v186, v176, v177
	v_cvt_pk_bf16_f32 v187, v178, v179
	global_store_dwordx4 v140, v[184:187], s[22:23] offset:256
	s_add_u32 s22, s64, 0x50000
	s_addc_u32 s23, s65, 0
	s_waitcnt vmcnt(14)
	v_lshlrev_b32_e32 v164, 16, v236
	v_and_b32_e32 v165, 0xffff0000, v236
	v_lshlrev_b32_e32 v166, 16, v237
	v_and_b32_e32 v167, 0xffff0000, v237
	v_lshlrev_b32_e32 v168, 16, v238
	v_and_b32_e32 v169, 0xffff0000, v238
	v_lshlrev_b32_e32 v170, 16, v239
	v_and_b32_e32 v171, 0xffff0000, v239
	v_pk_mul_f32 v[28:29], v[28:29], v[134:135] op_sel_hi:[1,0]
	v_pk_mul_f32 v[30:31], v[30:31], v[134:135] op_sel_hi:[1,0]
	v_pk_mul_f32 v[16:17], v[16:17], v[134:135] op_sel_hi:[1,0]
	v_pk_mul_f32 v[18:19], v[18:19], v[134:135] op_sel_hi:[1,0]
	v_pk_fma_f32 v[164:165], v[28:29], v[148:149], v[164:165]
	v_pk_fma_f32 v[166:167], v[30:31], v[150:151], v[166:167]
	v_pk_fma_f32 v[168:169], v[16:17], v[152:153], v[168:169]
	v_pk_fma_f32 v[170:171], v[18:19], v[154:155], v[170:171]
	v_mul_f32_e32 v145, v164, v164
	v_fmac_f32_e32 v145, v165, v165
	v_fmac_f32_e32 v145, v166, v166
	v_fmac_f32_e32 v145, v167, v167
	v_fmac_f32_e32 v145, v168, v168
	v_fmac_f32_e32 v145, v169, v169
	v_fmac_f32_e32 v145, v170, v170
	v_fmac_f32_e32 v145, v171, v171
	v_cvt_pk_bf16_f32 v180, v164, v165
	v_cvt_pk_bf16_f32 v181, v166, v167
	v_cvt_pk_bf16_f32 v182, v168, v169
	v_cvt_pk_bf16_f32 v183, v170, v171
	global_store_dwordx4 v140, v[180:183], s[22:23]
	v_lshlrev_b32_e32 v172, 16, v240
	v_and_b32_e32 v173, 0xffff0000, v240
	v_lshlrev_b32_e32 v174, 16, v241
	v_and_b32_e32 v175, 0xffff0000, v241
	v_lshlrev_b32_e32 v176, 16, v242
	v_and_b32_e32 v177, 0xffff0000, v242
	v_lshlrev_b32_e32 v178, 16, v243
	v_and_b32_e32 v179, 0xffff0000, v243
	v_pk_mul_f32 v[20:21], v[20:21], v[134:135] op_sel_hi:[1,0]
	v_pk_mul_f32 v[22:23], v[22:23], v[134:135] op_sel_hi:[1,0]
	v_pk_mul_f32 v[24:25], v[24:25], v[134:135] op_sel_hi:[1,0]
	v_pk_mul_f32 v[26:27], v[26:27], v[134:135] op_sel_hi:[1,0]
	v_pk_fma_f32 v[172:173], v[20:21], v[156:157], v[172:173]
	v_pk_fma_f32 v[174:175], v[22:23], v[158:159], v[174:175]
	v_pk_fma_f32 v[176:177], v[24:25], v[160:161], v[176:177]
	v_pk_fma_f32 v[178:179], v[26:27], v[162:163], v[178:179]
	v_fmac_f32_e32 v145, v172, v172
	v_fmac_f32_e32 v145, v173, v173
	v_fmac_f32_e32 v145, v174, v174
	v_fmac_f32_e32 v145, v175, v175
	v_fmac_f32_e32 v145, v176, v176
	v_fmac_f32_e32 v145, v177, v177
	v_fmac_f32_e32 v145, v178, v178
	v_fmac_f32_e32 v145, v179, v179
	v_cvt_pk_bf16_f32 v184, v172, v173
	v_cvt_pk_bf16_f32 v185, v174, v175
	v_cvt_pk_bf16_f32 v186, v176, v177
	v_cvt_pk_bf16_f32 v187, v178, v179
	global_store_dwordx4 v140, v[184:187], s[22:23] offset:256
	s_add_u32 s22, s64, 0x58000
	s_addc_u32 s23, s65, 0
	s_waitcnt vmcnt(14)
	v_lshlrev_b32_e32 v164, 16, v244
	v_and_b32_e32 v165, 0xffff0000, v244
	v_lshlrev_b32_e32 v166, 16, v245
	v_and_b32_e32 v167, 0xffff0000, v245
	v_lshlrev_b32_e32 v168, 16, v246
	v_and_b32_e32 v169, 0xffff0000, v246
	v_lshlrev_b32_e32 v170, 16, v247
	v_and_b32_e32 v171, 0xffff0000, v247
	v_pk_mul_f32 v[12:13], v[12:13], v[134:135] op_sel:[0,1] op_sel_hi:[1,1]
	v_pk_mul_f32 v[14:15], v[14:15], v[134:135] op_sel:[0,1] op_sel_hi:[1,1]
	v_pk_mul_f32 v[0:1], v[0:1], v[134:135] op_sel:[0,1] op_sel_hi:[1,1]
	v_pk_mul_f32 v[2:3], v[2:3], v[134:135] op_sel:[0,1] op_sel_hi:[1,1]
	v_pk_fma_f32 v[164:165], v[12:13], v[148:149], v[164:165]
	v_pk_fma_f32 v[166:167], v[14:15], v[150:151], v[166:167]
	v_pk_fma_f32 v[168:169], v[0:1], v[152:153], v[168:169]
	v_pk_fma_f32 v[170:171], v[2:3], v[154:155], v[170:171]
	v_mul_f32_e32 v146, v164, v164
	v_fmac_f32_e32 v146, v165, v165
	v_fmac_f32_e32 v146, v166, v166
	v_fmac_f32_e32 v146, v167, v167
	v_fmac_f32_e32 v146, v168, v168
	v_fmac_f32_e32 v146, v169, v169
	v_fmac_f32_e32 v146, v170, v170
	v_fmac_f32_e32 v146, v171, v171
	v_cvt_pk_bf16_f32 v180, v164, v165
	v_cvt_pk_bf16_f32 v181, v166, v167
	v_cvt_pk_bf16_f32 v182, v168, v169
	v_cvt_pk_bf16_f32 v183, v170, v171
	global_store_dwordx4 v140, v[180:183], s[22:23]
	v_lshlrev_b32_e32 v172, 16, v248
	v_and_b32_e32 v173, 0xffff0000, v248
	v_lshlrev_b32_e32 v174, 16, v249
	v_and_b32_e32 v175, 0xffff0000, v249
	v_lshlrev_b32_e32 v176, 16, v250
	v_and_b32_e32 v177, 0xffff0000, v250
	v_lshlrev_b32_e32 v178, 16, v251
	v_and_b32_e32 v179, 0xffff0000, v251
	v_pk_mul_f32 v[4:5], v[4:5], v[134:135] op_sel:[0,1] op_sel_hi:[1,1]
	v_pk_mul_f32 v[6:7], v[6:7], v[134:135] op_sel:[0,1] op_sel_hi:[1,1]
	v_pk_mul_f32 v[8:9], v[8:9], v[134:135] op_sel:[0,1] op_sel_hi:[1,1]
	v_pk_mul_f32 v[10:11], v[10:11], v[134:135] op_sel:[0,1] op_sel_hi:[1,1]
	v_pk_fma_f32 v[172:173], v[4:5], v[156:157], v[172:173]
	v_pk_fma_f32 v[174:175], v[6:7], v[158:159], v[174:175]
	v_pk_fma_f32 v[176:177], v[8:9], v[160:161], v[176:177]
	v_pk_fma_f32 v[178:179], v[10:11], v[162:163], v[178:179]
	v_fmac_f32_e32 v146, v172, v172
	v_fmac_f32_e32 v146, v173, v173
	v_fmac_f32_e32 v146, v174, v174
	v_fmac_f32_e32 v146, v175, v175
	v_fmac_f32_e32 v146, v176, v176
	v_fmac_f32_e32 v146, v177, v177
	v_fmac_f32_e32 v146, v178, v178
	v_fmac_f32_e32 v146, v179, v179
	v_cvt_pk_bf16_f32 v184, v172, v173
	v_cvt_pk_bf16_f32 v185, v174, v175
	v_cvt_pk_bf16_f32 v186, v176, v177
	v_cvt_pk_bf16_f32 v187, v178, v179
	global_store_dwordx4 v140, v[184:187], s[22:23] offset:256
	v_mov_b32_e32 v148, v138
	v_mov_b32_e32 v149, v139
	v_mov_b32_e32 v150, v141
	v_mov_b32_e32 v151, v142
	v_mov_b32_e32 v152, v143
	v_mov_b32_e32 v153, v144
	v_mov_b32_e32 v154, v145
	v_mov_b32_e32 v155, v146
	v_xor_b32_e32 v138, 16, v137
	v_xor_b32_e32 v139, 32, v137
	v_lshlrev_b32_e32 v138, 2, v138
	v_lshlrev_b32_e32 v139, 2, v139
	ds_bpermute_b32 v164, v138, v148
	ds_bpermute_b32 v165, v138, v149
	ds_bpermute_b32 v166, v138, v150
	ds_bpermute_b32 v167, v138, v151
	ds_bpermute_b32 v168, v138, v152
	ds_bpermute_b32 v169, v138, v153
	ds_bpermute_b32 v170, v138, v154
	ds_bpermute_b32 v171, v138, v155
	s_waitcnt lgkmcnt(0)
	v_add_f32_e32 v148, v148, v164
	v_add_f32_e32 v149, v149, v165
	v_add_f32_e32 v150, v150, v166
	v_add_f32_e32 v151, v151, v167
	v_add_f32_e32 v152, v152, v168
	v_add_f32_e32 v153, v153, v169
	v_add_f32_e32 v154, v154, v170
	v_add_f32_e32 v155, v155, v171
	ds_bpermute_b32 v164, v139, v148
	ds_bpermute_b32 v165, v139, v149
	ds_bpermute_b32 v166, v139, v150
	ds_bpermute_b32 v167, v139, v151
	ds_bpermute_b32 v168, v139, v152
	ds_bpermute_b32 v169, v139, v153
	ds_bpermute_b32 v170, v139, v154
	ds_bpermute_b32 v171, v139, v155
	s_waitcnt lgkmcnt(0)
	v_add_f32_e32 v148, v148, v164
	v_add_f32_e32 v149, v149, v165
	v_add_f32_e32 v150, v150, v166
	v_add_f32_e32 v151, v151, v167
	v_add_f32_e32 v152, v152, v168
	v_add_f32_e32 v153, v153, v169
	v_add_f32_e32 v154, v154, v170
	v_add_f32_e32 v155, v155, v171
	s_and_b32 s98, s2, 7
	s_lshl_b32 s98, s98, 3
	s_bfe_u32 s99, s2, 0x30003
	s_or_b32 s98, s98, s99
	s_lshr_b32 s99, s2, 6
	s_mul_i32 s99, s99, 0x42000
	s_lshl_b32 s98, s98, 10
	s_add_u32 s100, s62, s99
	s_addc_u32 s101, s63, 0
	s_add_u32 s100, s100, s98
	s_addc_u32 s101, s101, 0
	v_lshrrev_b32_e32 v158, 8, v136
	v_bfe_u32 v159, v136, 6, 2
	v_and_b32_e32 v160, 15, v136
	v_lshl_add_u32 v160, v158, 6, v160
	v_mul_u32_u24_e32 v159, 0x4200, v159
	v_add_u32_e32 v160, v160, v159
	v_lshlrev_b32_e32 v160, 2, v160
	v_bfe_u32 v161, v136, 4, 2
	v_cmp_eq_u32_e32 vcc, 0, v161
	s_and_saveexec_b64 s[0:1], vcc
	global_store_dword v160, v148, s[100:101]
	global_store_dword v160, v149, s[100:101] offset:64
	global_store_dword v160, v150, s[100:101] offset:128
	global_store_dword v160, v151, s[100:101] offset:192
	global_store_dword v160, v152, s[100:101] offset:512
	global_store_dword v160, v153, s[100:101] offset:576
	global_store_dword v160, v154, s[100:101] offset:640
	global_store_dword v160, v155, s[100:101] offset:704
	s_or_b64 exec, exec, s[0:1]
	v_bfe_u32 v183, v136, 1, 2
	v_lshrrev_b32_e32 v187, 6, v136
	v_lshlrev_b32_e32 v190, 11, v136
	v_lshrrev_b32_e32 v252, 1, v136
	v_and_b32_e32 v132, 48, v136
	v_and_b32_e32 v189, 63, v136
	v_lshrrev_b32_e32 v182, 3, v136
	v_lshlrev_b32_e32 v188, 2, v136
	v_lshl_add_u32 v186, v183, 6, 0
	v_and_b32_e32 v191, 15, v136
	v_cndmask_b32_e64 v1, 0, 1, s[8:9]
	v_mov_b32_e32 v0, v136
	v_cmp_ne_u32_e64 s[6:7], 1, v1
	s_andn2_b64 vcc, exec, s[8:9]
	s_cbranch_vccnz .LBB0_1254
	v_and_b32_e32 v4, 63, v0
	v_ashrrev_i32_e32 v0, 5, v0
	v_readlane_b32 s8, v253, 3
	v_and_b32_e32 v5, -2, v0
	v_lshlrev_b32_e32 v0, 4, v4
	v_mov_b32_e32 v1, 0
	v_readlane_b32 s9, v253, 4
	s_mov_b64 s[0:1], 0x3000
	v_readlane_b32 s12, v253, 7
	v_lshl_add_u64 v[2:3], s[8:9], 0, v[0:1]
	v_lshl_add_u64 v[16:17], v[2:3], 0, s[0:1]
	v_and_b32_e32 v2, 64, v137
	v_add_u32_e32 v2, 64, v2
	v_xor_b32_e32 v3, 32, v137
	v_cmp_lt_i32_e64 s[0:1], v3, v2
	v_mul_u32_u24_e32 v0, 0x4200, v4
	v_lshlrev_b32_e32 v0, 2, v0
	v_cndmask_b32_e64 v3, v137, v3, s[0:1]
	v_lshlrev_b32_e32 v50, 2, v3
	v_xor_b32_e32 v3, 16, v137
	v_cmp_lt_i32_e64 s[0:1], v3, v2
	v_readlane_b32 s13, v253, 8
	v_lshl_add_u64 v[18:19], s[44:45], 0, v[0:1]
	v_cndmask_b32_e64 v3, v137, v3, s[0:1]
	v_lshlrev_b32_e32 v51, 2, v3
	v_xor_b32_e32 v3, 8, v137
	v_cmp_lt_i32_e64 s[0:1], v3, v2
	v_lshlrev_b32_e32 v0, 3, v4
	v_cmp_gt_u32_e32 vcc, 16, v4
	v_cndmask_b32_e64 v3, v137, v3, s[0:1]
	v_lshlrev_b32_e32 v52, 2, v3
	v_xor_b32_e32 v3, 4, v137
	v_cmp_lt_i32_e64 s[0:1], v3, v2
	v_lshl_add_u64 v[20:21], s[64:65], 0, v[0:1]
	v_lshl_add_u64 v[22:23], s[60:61], 0, v[0:1]
	v_cndmask_b32_e64 v3, v137, v3, s[0:1]
	v_lshlrev_b32_e32 v53, 2, v3
	v_xor_b32_e32 v3, 2, v137
	v_cmp_lt_i32_e64 s[0:1], v3, v2
	v_lshl_add_u64 v[24:25], s[58:59], 0, v[0:1]
	v_lshl_add_u32 v26, s2, 4, v5
	v_cndmask_b32_e64 v3, v137, v3, s[0:1]
	v_lshlrev_b32_e32 v54, 2, v3
	v_xor_b32_e32 v3, 1, v137
	v_cmp_lt_i32_e64 s[0:1], v3, v2
	s_lshl_b32 s3, s38, 4
	v_mov_b32_e32 v56, 0x358637bd
	v_cndmask_b32_e64 v2, v137, v3, s[0:1]
	v_lshlrev_b32_e32 v55, 2, v2
	v_cmp_eq_u32_e64 s[0:1], 0, v4
	s_mov_b32 s12, 0x800000
	s_mov_b32 s13, s2
	v_readlane_b32 s10, v253, 5
	v_readlane_b32 s11, v253, 6
	v_readlane_b32 s14, v253, 9
	v_readlane_b32 s15, v253, 10
	v_readlane_b32 s16, v253, 11
	v_readlane_b32 s17, v253, 12
	v_readlane_b32 s18, v253, 13
	v_readlane_b32 s19, v253, 14
	v_readlane_b32 s20, v253, 15
	v_readlane_b32 s21, v253, 16
	v_readlane_b32 s22, v253, 17
	v_readlane_b32 s23, v253, 18
	s_addk_i32 s13, 0x400
	v_add_u32_e32 v26, 0x4000, v26
	s_cmpk_lt_i32 s13, 0x420
	s_cbranch_scc0 .LBB0_1254
	s_branch .LBB0_1246

.LBB0_1468:
	s_or_b64 exec, exec, s[0:1]
	s_and_b64 vcc, exec, s[6:7]
	s_waitcnt lgkmcnt(0)
	s_barrier
	s_and_b32 s99, s2, 7
	s_lshl_b32 s99, s99, 3
	s_bfe_u32 s100, s2, 0x30003
	s_or_b32 s99, s99, s100
	s_lshr_b32 s100, s2, 6
	v_and_b32_e32 v172, 0xff, v136
	v_lshrrev_b32_e32 v173, 8, v136
	v_mul_u32_u24_e32 v173, 0x84000, v173
	v_lshl_add_u32 v172, v172, 2, v173
	s_lshl_b32 s24, s99, 10
	s_add_u32 s18, s44, s24
	s_addc_u32 s19, s45, 0
	global_load_dword v164, v172, s[18:19]
	s_add_u32 s18, s18, 0x10800
	s_addc_u32 s19, s19, 0
	global_load_dword v165, v172, s[18:19]
	s_add_u32 s18, s18, 0x10800
	s_addc_u32 s19, s19, 0
	global_load_dword v166, v172, s[18:19]
	s_add_u32 s18, s18, 0x10800
	s_addc_u32 s19, s19, 0
	global_load_dword v167, v172, s[18:19]
	s_add_u32 s18, s18, 0x10800
	s_addc_u32 s19, s19, 0
	global_load_dword v168, v172, s[18:19]
	s_add_u32 s18, s18, 0x10800
	s_addc_u32 s19, s19, 0
	global_load_dword v169, v172, s[18:19]
	s_add_u32 s18, s18, 0x10800
	s_addc_u32 s19, s19, 0
	global_load_dword v170, v172, s[18:19]
	s_add_u32 s18, s18, 0x10800
	s_addc_u32 s19, s19, 0
	global_load_dword v171, v172, s[18:19]
	v_lshrrev_b32_e32 v141, 8, v136
	v_and_b32_e32 v142, 15, v136
	v_lshl_add_u32 v141, v141, 6, v142
	v_bfe_u32 v144, v136, 6, 2
	v_bfe_u32 v145, v136, 4, 2
	v_lshlrev_b32_e32 v144, 5, v144
	v_lshl_add_u32 v144, v145, 3, v144
	s_lshl_b32 s24, s100, 8
	v_add_u32_e32 v144, s24, v144
	s_lshl_b32 s25, s99, 8
	v_add_u32_e32 v145, s25, v141
	v_lshl_add_u32 v146, v145, 10, v144
	v_lshlrev_b32_e32 v139, 1, v146
	v_lshlrev_b32_e32 v140, 2, v146
	v_lshlrev_b32_e32 v138, 2, v144
	v_readlane_b32 s18, v253, 3
	v_readlane_b32 s19, v253, 4
	v_readlane_b32 s20, v254, 52
	v_readlane_b32 s21, v254, 53
	s_nop 4
	s_add_u32 s18, s18, 0x5000
	s_addc_u32 s19, s19, 0
	global_load_dwordx4 v[148:151], v138, s[18:19]
	global_load_dwordx4 v[152:155], v138, s[18:19] offset:16
	global_load_dwordx4 v[156:159], v138, s[18:19] offset:512
	global_load_dwordx4 v[160:163], v138, s[18:19] offset:528
	s_add_u32 s22, s64, 0x0
	s_addc_u32 s23, s65, 0
	global_load_dwordx4 v[188:191], v139, s[22:23] nt
	global_load_dwordx4 v[192:195], v139, s[22:23] offset:256 nt
	s_add_u32 s22, s64, 0x8000
	s_addc_u32 s23, s65, 0
	global_load_dwordx4 v[196:199], v139, s[22:23] nt
	global_load_dwordx4 v[200:203], v139, s[22:23] offset:256 nt
	s_add_u32 s22, s64, 0x10000
	s_addc_u32 s23, s65, 0
	global_load_dwordx4 v[204:207], v139, s[22:23] nt
	global_load_dwordx4 v[208:211], v139, s[22:23] offset:256 nt
	s_add_u32 s22, s64, 0x18000
	s_addc_u32 s23, s65, 0
	global_load_dwordx4 v[212:215], v139, s[22:23] nt
	global_load_dwordx4 v[216:219], v139, s[22:23] offset:256 nt
	s_add_u32 s22, s64, 0x40000
	s_addc_u32 s23, s65, 0
	global_load_dwordx4 v[220:223], v139, s[22:23] nt
	global_load_dwordx4 v[224:227], v139, s[22:23] offset:256 nt
	s_add_u32 s22, s64, 0x48000
	s_addc_u32 s23, s65, 0
	global_load_dwordx4 v[228:231], v139, s[22:23] nt
	global_load_dwordx4 v[232:235], v139, s[22:23] offset:256 nt
	s_add_u32 s22, s64, 0x50000
	s_addc_u32 s23, s65, 0
	global_load_dwordx4 v[236:239], v139, s[22:23] nt
	global_load_dwordx4 v[240:243], v139, s[22:23] offset:256 nt
	s_add_u32 s22, s64, 0x58000
	s_addc_u32 s23, s65, 0
	global_load_dwordx4 v[244:247], v139, s[22:23] nt
	global_load_dwordx4 v[248:251], v139, s[22:23] offset:256 nt
	s_waitcnt vmcnt(20)
	v_add_f32_e32 v164, v164, v165
	v_add_f32_e32 v164, v164, v166
	v_add_f32_e32 v164, v164, v167
	v_add_f32_e32 v164, v164, v168
	v_add_f32_e32 v164, v164, v169
	v_add_f32_e32 v164, v164, v170
	v_add_f32_e32 v164, v164, v171
	v_lshlrev_b32_e32 v173, 2, v136
	ds_write_b32 v173, v164
	s_waitcnt lgkmcnt(0)
	s_barrier
	v_lshlrev_b32_e32 v142, 2, v141
	ds_read_b32 v128, v142 offset:0
	ds_read_b32 v174, v142 offset:1024
	ds_read_b32 v129, v142 offset:64
	ds_read_b32 v175, v142 offset:1088
	ds_read_b32 v130, v142 offset:128
	ds_read_b32 v176, v142 offset:1152
	ds_read_b32 v131, v142 offset:192
	ds_read_b32 v177, v142 offset:1216
	ds_read_b32 v132, v142 offset:512
	ds_read_b32 v178, v142 offset:1536
	ds_read_b32 v133, v142 offset:576
	ds_read_b32 v179, v142 offset:1600
	ds_read_b32 v134, v142 offset:640
	ds_read_b32 v180, v142 offset:1664
	ds_read_b32 v135, v142 offset:704
	ds_read_b32 v181, v142 offset:1728
	s_waitcnt lgkmcnt(0)
	s_mov_b32 s101, 0x3a800000
	v_mov_b32_e32 v143, 0x358637bd
	v_add_f32_e32 v128, v128, v174
	v_add_f32_e32 v129, v129, v175
	v_add_f32_e32 v130, v130, v176
	v_add_f32_e32 v131, v131, v177
	v_add_f32_e32 v132, v132, v178
	v_add_f32_e32 v133, v133, v179
	v_add_f32_e32 v134, v134, v180
	v_add_f32_e32 v135, v135, v181
	v_fma_f32 v128, v128, s101, v143
	v_fma_f32 v129, v129, s101, v143
	v_fma_f32 v130, v130, s101, v143
	v_fma_f32 v131, v131, s101, v143
	v_fma_f32 v132, v132, s101, v143
	v_fma_f32 v133, v133, s101, v143
	v_fma_f32 v134, v134, s101, v143
	v_fma_f32 v135, v135, s101, v143
	v_rsq_f32_e32 v128, v128
	v_rsq_f32_e32 v129, v129
	v_rsq_f32_e32 v130, v130
	v_rsq_f32_e32 v131, v131
	v_rsq_f32_e32 v132, v132
	v_rsq_f32_e32 v133, v133
	v_rsq_f32_e32 v134, v134
	v_rsq_f32_e32 v135, v135
	s_add_u32 s22, s20, 0x0
	s_addc_u32 s23, s21, 0
	s_waitcnt vmcnt(14)
	v_lshlrev_b32_e32 v164, 16, v188
	v_and_b32_e32 v165, 0xffff0000, v188
	v_lshlrev_b32_e32 v166, 16, v189
	v_and_b32_e32 v167, 0xffff0000, v189
	v_lshlrev_b32_e32 v168, 16, v190
	v_and_b32_e32 v169, 0xffff0000, v190
	v_lshlrev_b32_e32 v170, 16, v191
	v_and_b32_e32 v171, 0xffff0000, v191
	v_pk_mul_f32 v[124:125], v[124:125], v[128:129] op_sel_hi:[1,0]
	v_pk_mul_f32 v[126:127], v[126:127], v[128:129] op_sel_hi:[1,0]
	v_pk_mul_f32 v[112:113], v[112:113], v[128:129] op_sel_hi:[1,0]
	v_pk_mul_f32 v[114:115], v[114:115], v[128:129] op_sel_hi:[1,0]
	v_pk_fma_f32 v[164:165], v[124:125], v[148:149], v[164:165]
	v_pk_fma_f32 v[166:167], v[126:127], v[150:151], v[166:167]
	v_pk_fma_f32 v[168:169], v[112:113], v[152:153], v[168:169]
	v_pk_fma_f32 v[170:171], v[114:115], v[154:155], v[170:171]
	global_store_dwordx4 v140, v[164:167], s[22:23]
	global_store_dwordx4 v140, v[168:171], s[22:23] offset:16
	v_lshlrev_b32_e32 v172, 16, v192
	v_and_b32_e32 v173, 0xffff0000, v192
	v_lshlrev_b32_e32 v174, 16, v193
	v_and_b32_e32 v175, 0xffff0000, v193
	v_lshlrev_b32_e32 v176, 16, v194
	v_and_b32_e32 v177, 0xffff0000, v194
	v_lshlrev_b32_e32 v178, 16, v195
	v_and_b32_e32 v179, 0xffff0000, v195
	v_pk_mul_f32 v[120:121], v[120:121], v[128:129] op_sel_hi:[1,0]
	v_pk_mul_f32 v[122:123], v[122:123], v[128:129] op_sel_hi:[1,0]
	v_pk_mul_f32 v[116:117], v[116:117], v[128:129] op_sel_hi:[1,0]
	v_pk_mul_f32 v[118:119], v[118:119], v[128:129] op_sel_hi:[1,0]
	v_pk_fma_f32 v[172:173], v[120:121], v[156:157], v[172:173]
	v_pk_fma_f32 v[174:175], v[122:123], v[158:159], v[174:175]
	v_pk_fma_f32 v[176:177], v[116:117], v[160:161], v[176:177]
	v_pk_fma_f32 v[178:179], v[118:119], v[162:163], v[178:179]
	global_store_dwordx4 v140, v[172:175], s[22:23] offset:512
	global_store_dwordx4 v140, v[176:179], s[22:23] offset:528
	s_add_u32 s22, s20, 0x10000
	s_addc_u32 s23, s21, 0
	s_waitcnt vmcnt(16)
	v_lshlrev_b32_e32 v180, 16, v196
	v_and_b32_e32 v181, 0xffff0000, v196
	v_lshlrev_b32_e32 v182, 16, v197
	v_and_b32_e32 v183, 0xffff0000, v197
	v_lshlrev_b32_e32 v184, 16, v198
	v_and_b32_e32 v185, 0xffff0000, v198
	v_lshlrev_b32_e32 v186, 16, v199
	v_and_b32_e32 v187, 0xffff0000, v199
	v_pk_mul_f32 v[108:109], v[108:109], v[128:129] op_sel:[0,1] op_sel_hi:[1,1]
	v_pk_mul_f32 v[110:111], v[110:111], v[128:129] op_sel:[0,1] op_sel_hi:[1,1]
	v_pk_mul_f32 v[96:97], v[96:97], v[128:129] op_sel:[0,1] op_sel_hi:[1,1]
	v_pk_mul_f32 v[98:99], v[98:99], v[128:129] op_sel:[0,1] op_sel_hi:[1,1]
	v_pk_fma_f32 v[180:181], v[108:109], v[148:149], v[180:181]
	v_pk_fma_f32 v[182:183], v[110:111], v[150:151], v[182:183]
	v_pk_fma_f32 v[184:185], v[96:97], v[152:153], v[184:185]
	v_pk_fma_f32 v[186:187], v[98:99], v[154:155], v[186:187]
	global_store_dwordx4 v140, v[180:183], s[22:23]
	global_store_dwordx4 v140, v[184:187], s[22:23] offset:16
	v_lshlrev_b32_e32 v164, 16, v200
	v_and_b32_e32 v165, 0xffff0000, v200
	v_lshlrev_b32_e32 v166, 16, v201
	v_and_b32_e32 v167, 0xffff0000, v201
	v_lshlrev_b32_e32 v168, 16, v202
	v_and_b32_e32 v169, 0xffff0000, v202
	v_lshlrev_b32_e32 v170, 16, v203
	v_and_b32_e32 v171, 0xffff0000, v203
	v_pk_mul_f32 v[100:101], v[100:101], v[128:129] op_sel:[0,1] op_sel_hi:[1,1]
	v_pk_mul_f32 v[102:103], v[102:103], v[128:129] op_sel:[0,1] op_sel_hi:[1,1]
	v_pk_mul_f32 v[104:105], v[104:105], v[128:129] op_sel:[0,1] op_sel_hi:[1,1]
	v_pk_mul_f32 v[106:107], v[106:107], v[128:129] op_sel:[0,1] op_sel_hi:[1,1]
	v_pk_fma_f32 v[164:165], v[100:101], v[156:157], v[164:165]
	v_pk_fma_f32 v[166:167], v[102:103], v[158:159], v[166:167]
	v_pk_fma_f32 v[168:169], v[104:105], v[160:161], v[168:169]
	v_pk_fma_f32 v[170:171], v[106:107], v[162:163], v[170:171]
	global_store_dwordx4 v140, v[164:167], s[22:23] offset:512
	global_store_dwordx4 v140, v[168:171], s[22:23] offset:528
	s_add_u32 s22, s20, 0x20000
	s_addc_u32 s23, s21, 0
	s_waitcnt vmcnt(18)
	v_lshlrev_b32_e32 v172, 16, v204
	v_and_b32_e32 v173, 0xffff0000, v204
	v_lshlrev_b32_e32 v174, 16, v205
	v_and_b32_e32 v175, 0xffff0000, v205
	v_lshlrev_b32_e32 v176, 16, v206
	v_and_b32_e32 v177, 0xffff0000, v206
	v_lshlrev_b32_e32 v178, 16, v207
	v_and_b32_e32 v179, 0xffff0000, v207
	v_pk_mul_f32 v[92:93], v[92:93], v[130:131] op_sel_hi:[1,0]
	v_pk_mul_f32 v[94:95], v[94:95], v[130:131] op_sel_hi:[1,0]
	v_pk_mul_f32 v[80:81], v[80:81], v[130:131] op_sel_hi:[1,0]
	v_pk_mul_f32 v[82:83], v[82:83], v[130:131] op_sel_hi:[1,0]
	v_pk_fma_f32 v[172:173], v[92:93], v[148:149], v[172:173]
	v_pk_fma_f32 v[174:175], v[94:95], v[150:151], v[174:175]
	v_pk_fma_f32 v[176:177], v[80:81], v[152:153], v[176:177]
	v_pk_fma_f32 v[178:179], v[82:83], v[154:155], v[178:179]
	global_store_dwordx4 v140, v[172:175], s[22:23]
	global_store_dwordx4 v140, v[176:179], s[22:23] offset:16
	v_lshlrev_b32_e32 v180, 16, v208
	v_and_b32_e32 v181, 0xffff0000, v208
	v_lshlrev_b32_e32 v182, 16, v209
	v_and_b32_e32 v183, 0xffff0000, v209
	v_lshlrev_b32_e32 v184, 16, v210
	v_and_b32_e32 v185, 0xffff0000, v210
	v_lshlrev_b32_e32 v186, 16, v211
	v_and_b32_e32 v187, 0xffff0000, v211
	v_pk_mul_f32 v[84:85], v[84:85], v[130:131] op_sel_hi:[1,0]
	v_pk_mul_f32 v[86:87], v[86:87], v[130:131] op_sel_hi:[1,0]
	v_pk_mul_f32 v[88:89], v[88:89], v[130:131] op_sel_hi:[1,0]
	v_pk_mul_f32 v[90:91], v[90:91], v[130:131] op_sel_hi:[1,0]
	v_pk_fma_f32 v[180:181], v[84:85], v[156:157], v[180:181]
	v_pk_fma_f32 v[182:183], v[86:87], v[158:159], v[182:183]
	v_pk_fma_f32 v[184:185], v[88:89], v[160:161], v[184:185]
	v_pk_fma_f32 v[186:187], v[90:91], v[162:163], v[186:187]
	global_store_dwordx4 v140, v[180:183], s[22:23] offset:512
	global_store_dwordx4 v140, v[184:187], s[22:23] offset:528
	s_add_u32 s22, s20, 0x30000
	s_addc_u32 s23, s21, 0
	s_waitcnt vmcnt(20)
	v_lshlrev_b32_e32 v164, 16, v212
	v_and_b32_e32 v165, 0xffff0000, v212
	v_lshlrev_b32_e32 v166, 16, v213
	v_and_b32_e32 v167, 0xffff0000, v213
	v_lshlrev_b32_e32 v168, 16, v214
	v_and_b32_e32 v169, 0xffff0000, v214
	v_lshlrev_b32_e32 v170, 16, v215
	v_and_b32_e32 v171, 0xffff0000, v215
	v_pk_mul_f32 v[76:77], v[76:77], v[130:131] op_sel:[0,1] op_sel_hi:[1,1]
	v_pk_mul_f32 v[78:79], v[78:79], v[130:131] op_sel:[0,1] op_sel_hi:[1,1]
	v_pk_mul_f32 v[64:65], v[64:65], v[130:131] op_sel:[0,1] op_sel_hi:[1,1]
	v_pk_mul_f32 v[66:67], v[66:67], v[130:131] op_sel:[0,1] op_sel_hi:[1,1]
	v_pk_fma_f32 v[164:165], v[76:77], v[148:149], v[164:165]
	v_pk_fma_f32 v[166:167], v[78:79], v[150:151], v[166:167]
	v_pk_fma_f32 v[168:169], v[64:65], v[152:153], v[168:169]
	v_pk_fma_f32 v[170:171], v[66:67], v[154:155], v[170:171]
	global_store_dwordx4 v140, v[164:167], s[22:23]
	global_store_dwordx4 v140, v[168:171], s[22:23] offset:16
	v_lshlrev_b32_e32 v172, 16, v216
	v_and_b32_e32 v173, 0xffff0000, v216
	v_lshlrev_b32_e32 v174, 16, v217
	v_and_b32_e32 v175, 0xffff0000, v217
	v_lshlrev_b32_e32 v176, 16, v218
	v_and_b32_e32 v177, 0xffff0000, v218
	v_lshlrev_b32_e32 v178, 16, v219
	v_and_b32_e32 v179, 0xffff0000, v219
	v_pk_mul_f32 v[68:69], v[68:69], v[130:131] op_sel:[0,1] op_sel_hi:[1,1]
	v_pk_mul_f32 v[70:71], v[70:71], v[130:131] op_sel:[0,1] op_sel_hi:[1,1]
	v_pk_mul_f32 v[72:73], v[72:73], v[130:131] op_sel:[0,1] op_sel_hi:[1,1]
	v_pk_mul_f32 v[74:75], v[74:75], v[130:131] op_sel:[0,1] op_sel_hi:[1,1]
	v_pk_fma_f32 v[172:173], v[68:69], v[156:157], v[172:173]
	v_pk_fma_f32 v[174:175], v[70:71], v[158:159], v[174:175]
	v_pk_fma_f32 v[176:177], v[72:73], v[160:161], v[176:177]
	v_pk_fma_f32 v[178:179], v[74:75], v[162:163], v[178:179]
	global_store_dwordx4 v140, v[172:175], s[22:23] offset:512
	global_store_dwordx4 v140, v[176:179], s[22:23] offset:528
	s_add_u32 s22, s20, 0x80000
	s_addc_u32 s23, s21, 0
	s_waitcnt vmcnt(22)
	v_lshlrev_b32_e32 v180, 16, v220
	v_and_b32_e32 v181, 0xffff0000, v220
	v_lshlrev_b32_e32 v182, 16, v221
	v_and_b32_e32 v183, 0xffff0000, v221
	v_lshlrev_b32_e32 v184, 16, v222
	v_and_b32_e32 v185, 0xffff0000, v222
	v_lshlrev_b32_e32 v186, 16, v223
	v_and_b32_e32 v187, 0xffff0000, v223
	v_pk_mul_f32 v[60:61], v[60:61], v[132:133] op_sel_hi:[1,0]
	v_pk_mul_f32 v[62:63], v[62:63], v[132:133] op_sel_hi:[1,0]
	v_pk_mul_f32 v[48:49], v[48:49], v[132:133] op_sel_hi:[1,0]
	v_pk_mul_f32 v[50:51], v[50:51], v[132:133] op_sel_hi:[1,0]
	v_pk_fma_f32 v[180:181], v[60:61], v[148:149], v[180:181]
	v_pk_fma_f32 v[182:183], v[62:63], v[150:151], v[182:183]
	v_pk_fma_f32 v[184:185], v[48:49], v[152:153], v[184:185]
	v_pk_fma_f32 v[186:187], v[50:51], v[154:155], v[186:187]
	global_store_dwordx4 v140, v[180:183], s[22:23]
	global_store_dwordx4 v140, v[184:187], s[22:23] offset:16
	v_lshlrev_b32_e32 v164, 16, v224
	v_and_b32_e32 v165, 0xffff0000, v224
	v_lshlrev_b32_e32 v166, 16, v225
	v_and_b32_e32 v167, 0xffff0000, v225
	v_lshlrev_b32_e32 v168, 16, v226
	v_and_b32_e32 v169, 0xffff0000, v226
	v_lshlrev_b32_e32 v170, 16, v227
	v_and_b32_e32 v171, 0xffff0000, v227
	v_pk_mul_f32 v[52:53], v[52:53], v[132:133] op_sel_hi:[1,0]
	v_pk_mul_f32 v[54:55], v[54:55], v[132:133] op_sel_hi:[1,0]
	v_pk_mul_f32 v[56:57], v[56:57], v[132:133] op_sel_hi:[1,0]
	v_pk_mul_f32 v[58:59], v[58:59], v[132:133] op_sel_hi:[1,0]
	v_pk_fma_f32 v[164:165], v[52:53], v[156:157], v[164:165]
	v_pk_fma_f32 v[166:167], v[54:55], v[158:159], v[166:167]
	v_pk_fma_f32 v[168:169], v[56:57], v[160:161], v[168:169]
	v_pk_fma_f32 v[170:171], v[58:59], v[162:163], v[170:171]
	global_store_dwordx4 v140, v[164:167], s[22:23] offset:512
	global_store_dwordx4 v140, v[168:171], s[22:23] offset:528
	s_add_u32 s22, s20, 0x90000
	s_addc_u32 s23, s21, 0
	s_waitcnt vmcnt(24)
	v_lshlrev_b32_e32 v172, 16, v228
	v_and_b32_e32 v173, 0xffff0000, v228
	v_lshlrev_b32_e32 v174, 16, v229
	v_and_b32_e32 v175, 0xffff0000, v229
	v_lshlrev_b32_e32 v176, 16, v230
	v_and_b32_e32 v177, 0xffff0000, v230
	v_lshlrev_b32_e32 v178, 16, v231
	v_and_b32_e32 v179, 0xffff0000, v231
	v_pk_mul_f32 v[44:45], v[44:45], v[132:133] op_sel:[0,1] op_sel_hi:[1,1]
	v_pk_mul_f32 v[46:47], v[46:47], v[132:133] op_sel:[0,1] op_sel_hi:[1,1]
	v_pk_mul_f32 v[32:33], v[32:33], v[132:133] op_sel:[0,1] op_sel_hi:[1,1]
	v_pk_mul_f32 v[34:35], v[34:35], v[132:133] op_sel:[0,1] op_sel_hi:[1,1]
	v_pk_fma_f32 v[172:173], v[44:45], v[148:149], v[172:173]
	v_pk_fma_f32 v[174:175], v[46:47], v[150:151], v[174:175]
	v_pk_fma_f32 v[176:177], v[32:33], v[152:153], v[176:177]
	v_pk_fma_f32 v[178:179], v[34:35], v[154:155], v[178:179]
	global_store_dwordx4 v140, v[172:175], s[22:23]
	global_store_dwordx4 v140, v[176:179], s[22:23] offset:16
	v_lshlrev_b32_e32 v180, 16, v232
	v_and_b32_e32 v181, 0xffff0000, v232
	v_lshlrev_b32_e32 v182, 16, v233
	v_and_b32_e32 v183, 0xffff0000, v233
	v_lshlrev_b32_e32 v184, 16, v234
	v_and_b32_e32 v185, 0xffff0000, v234
	v_lshlrev_b32_e32 v186, 16, v235
	v_and_b32_e32 v187, 0xffff0000, v235
	v_pk_mul_f32 v[36:37], v[36:37], v[132:133] op_sel:[0,1] op_sel_hi:[1,1]
	v_pk_mul_f32 v[38:39], v[38:39], v[132:133] op_sel:[0,1] op_sel_hi:[1,1]
	v_pk_mul_f32 v[40:41], v[40:41], v[132:133] op_sel:[0,1] op_sel_hi:[1,1]
	v_pk_mul_f32 v[42:43], v[42:43], v[132:133] op_sel:[0,1] op_sel_hi:[1,1]
	v_pk_fma_f32 v[180:181], v[36:37], v[156:157], v[180:181]
	v_pk_fma_f32 v[182:183], v[38:39], v[158:159], v[182:183]
	v_pk_fma_f32 v[184:185], v[40:41], v[160:161], v[184:185]
	v_pk_fma_f32 v[186:187], v[42:43], v[162:163], v[186:187]
	global_store_dwordx4 v140, v[180:183], s[22:23] offset:512
	global_store_dwordx4 v140, v[184:187], s[22:23] offset:528
	s_add_u32 s22, s20, 0xa0000
	s_addc_u32 s23, s21, 0
	s_waitcnt vmcnt(26)
	v_lshlrev_b32_e32 v164, 16, v236
	v_and_b32_e32 v165, 0xffff0000, v236
	v_lshlrev_b32_e32 v166, 16, v237
	v_and_b32_e32 v167, 0xffff0000, v237
	v_lshlrev_b32_e32 v168, 16, v238
	v_and_b32_e32 v169, 0xffff0000, v238
	v_lshlrev_b32_e32 v170, 16, v239
	v_and_b32_e32 v171, 0xffff0000, v239
	v_pk_mul_f32 v[28:29], v[28:29], v[134:135] op_sel_hi:[1,0]
	v_pk_mul_f32 v[30:31], v[30:31], v[134:135] op_sel_hi:[1,0]
	v_pk_mul_f32 v[16:17], v[16:17], v[134:135] op_sel_hi:[1,0]
	v_pk_mul_f32 v[18:19], v[18:19], v[134:135] op_sel_hi:[1,0]
	v_pk_fma_f32 v[164:165], v[28:29], v[148:149], v[164:165]
	v_pk_fma_f32 v[166:167], v[30:31], v[150:151], v[166:167]
	v_pk_fma_f32 v[168:169], v[16:17], v[152:153], v[168:169]
	v_pk_fma_f32 v[170:171], v[18:19], v[154:155], v[170:171]
	global_store_dwordx4 v140, v[164:167], s[22:23]
	global_store_dwordx4 v140, v[168:171], s[22:23] offset:16
	v_lshlrev_b32_e32 v172, 16, v240
	v_and_b32_e32 v173, 0xffff0000, v240
	v_lshlrev_b32_e32 v174, 16, v241
	v_and_b32_e32 v175, 0xffff0000, v241
	v_lshlrev_b32_e32 v176, 16, v242
	v_and_b32_e32 v177, 0xffff0000, v242
	v_lshlrev_b32_e32 v178, 16, v243
	v_and_b32_e32 v179, 0xffff0000, v243
	v_pk_mul_f32 v[20:21], v[20:21], v[134:135] op_sel_hi:[1,0]
	v_pk_mul_f32 v[22:23], v[22:23], v[134:135] op_sel_hi:[1,0]
	v_pk_mul_f32 v[24:25], v[24:25], v[134:135] op_sel_hi:[1,0]
	v_pk_mul_f32 v[26:27], v[26:27], v[134:135] op_sel_hi:[1,0]
	v_pk_fma_f32 v[172:173], v[20:21], v[156:157], v[172:173]
	v_pk_fma_f32 v[174:175], v[22:23], v[158:159], v[174:175]
	v_pk_fma_f32 v[176:177], v[24:25], v[160:161], v[176:177]
	v_pk_fma_f32 v[178:179], v[26:27], v[162:163], v[178:179]
	global_store_dwordx4 v140, v[172:175], s[22:23] offset:512
	global_store_dwordx4 v140, v[176:179], s[22:23] offset:528
	s_add_u32 s22, s20, 0xb0000
	s_addc_u32 s23, s21, 0
	s_waitcnt vmcnt(28)
	v_lshlrev_b32_e32 v180, 16, v244
	v_and_b32_e32 v181, 0xffff0000, v244
	v_lshlrev_b32_e32 v182, 16, v245
	v_and_b32_e32 v183, 0xffff0000, v245
	v_lshlrev_b32_e32 v184, 16, v246
	v_and_b32_e32 v185, 0xffff0000, v246
	v_lshlrev_b32_e32 v186, 16, v247
	v_and_b32_e32 v187, 0xffff0000, v247
	v_pk_mul_f32 v[12:13], v[12:13], v[134:135] op_sel:[0,1] op_sel_hi:[1,1]
	v_pk_mul_f32 v[14:15], v[14:15], v[134:135] op_sel:[0,1] op_sel_hi:[1,1]
	v_pk_mul_f32 v[0:1], v[0:1], v[134:135] op_sel:[0,1] op_sel_hi:[1,1]
	v_pk_mul_f32 v[2:3], v[2:3], v[134:135] op_sel:[0,1] op_sel_hi:[1,1]
	v_pk_fma_f32 v[180:181], v[12:13], v[148:149], v[180:181]
	v_pk_fma_f32 v[182:183], v[14:15], v[150:151], v[182:183]
	v_pk_fma_f32 v[184:185], v[0:1], v[152:153], v[184:185]
	v_pk_fma_f32 v[186:187], v[2:3], v[154:155], v[186:187]
	global_store_dwordx4 v140, v[180:183], s[22:23]
	global_store_dwordx4 v140, v[184:187], s[22:23] offset:16
	v_lshlrev_b32_e32 v164, 16, v248
	v_and_b32_e32 v165, 0xffff0000, v248
	v_lshlrev_b32_e32 v166, 16, v249
	v_and_b32_e32 v167, 0xffff0000, v249
	v_lshlrev_b32_e32 v168, 16, v250
	v_and_b32_e32 v169, 0xffff0000, v250
	v_lshlrev_b32_e32 v170, 16, v251
	v_and_b32_e32 v171, 0xffff0000, v251
	v_pk_mul_f32 v[4:5], v[4:5], v[134:135] op_sel:[0,1] op_sel_hi:[1,1]
	v_pk_mul_f32 v[6:7], v[6:7], v[134:135] op_sel:[0,1] op_sel_hi:[1,1]
	v_pk_mul_f32 v[8:9], v[8:9], v[134:135] op_sel:[0,1] op_sel_hi:[1,1]
	v_pk_mul_f32 v[10:11], v[10:11], v[134:135] op_sel:[0,1] op_sel_hi:[1,1]
	v_pk_fma_f32 v[164:165], v[4:5], v[156:157], v[164:165]
	v_pk_fma_f32 v[166:167], v[6:7], v[158:159], v[166:167]
	v_pk_fma_f32 v[168:169], v[8:9], v[160:161], v[168:169]
	v_pk_fma_f32 v[170:171], v[10:11], v[162:163], v[170:171]
	global_store_dwordx4 v140, v[164:167], s[22:23] offset:512
	global_store_dwordx4 v140, v[168:171], s[22:23] offset:528
	s_addk_i32 s2, 0x400
	s_cmpk_ge_u32 s2, 0x420
	s_cselect_b64 vcc, -1, 0
	s_cbranch_vccnz .LBB0_1475
	v_and_b32_e32 v4, 63, v136
	v_ashrrev_i32_e32 v0, 5, v136
	v_readlane_b32 s4, v253, 3
	v_and_b32_e32 v5, -2, v0
	v_lshlrev_b32_e32 v0, 4, v4
	v_mov_b32_e32 v1, 0
	v_readlane_b32 s5, v253, 4
	s_mov_b64 s[0:1], 0x5000
	v_xor_b32_e32 v6, 32, v137
	v_lshl_add_u64 v[2:3], s[4:5], 0, v[0:1]
	v_lshl_add_u64 v[16:17], v[2:3], 0, s[0:1]
	v_and_b32_e32 v3, 64, v137
	v_add_u32_e32 v3, 64, v3
	v_cmp_lt_i32_e64 s[0:1], v6, v3
	v_readlane_b32 s6, v253, 5
	v_readlane_b32 s7, v253, 6
	v_cndmask_b32_e64 v6, v137, v6, s[0:1]
	v_lshlrev_b32_e32 v29, 2, v6
	v_xor_b32_e32 v6, 16, v137
	v_cmp_lt_i32_e64 s[0:1], v6, v3
	v_readlane_b32 s8, v253, 7
	v_readlane_b32 s9, v253, 8
	v_cndmask_b32_e64 v6, v137, v6, s[0:1]
	v_lshlrev_b32_e32 v50, 2, v6
	v_xor_b32_e32 v6, 8, v137
	v_cmp_lt_i32_e64 s[0:1], v6, v3
	v_readlane_b32 s10, v253, 9
	v_readlane_b32 s11, v253, 10
	v_cndmask_b32_e64 v6, v137, v6, s[0:1]
	v_lshlrev_b32_e32 v51, 2, v6
	v_xor_b32_e32 v6, 4, v137
	v_cmp_lt_i32_e64 s[0:1], v6, v3
	v_readlane_b32 s12, v253, 11
	v_readlane_b32 s13, v253, 12
	v_cndmask_b32_e64 v6, v137, v6, s[0:1]
	v_lshlrev_b32_e32 v52, 2, v6
	v_xor_b32_e32 v6, 2, v137
	v_cmp_lt_i32_e64 s[0:1], v6, v3
	v_readlane_b32 s14, v253, 13
	v_readlane_b32 s15, v253, 14
	v_cndmask_b32_e64 v6, v137, v6, s[0:1]
	v_lshlrev_b32_e32 v53, 2, v6
	v_xor_b32_e32 v6, 1, v137
	v_cmp_lt_i32_e64 s[0:1], v6, v3
	v_readlane_b32 s16, v253, 15
	v_readlane_b32 s17, v253, 16
	v_readlane_b32 s18, v253, 17
	v_readlane_b32 s19, v253, 18
	v_mul_u32_u24_e32 v2, 0x4200, v4
	v_cndmask_b32_e64 v3, v137, v6, s[0:1]
	v_lshlrev_b32_e32 v54, 2, v3
	v_lshlrev_b32_e32 v2, 2, v2
	v_mov_b32_e32 v3, v1
	v_readlane_b32 s4, v254, 52
	v_lshl_add_u64 v[18:19], s[44:45], 0, v[2:3]
	v_lshlrev_b32_e32 v2, 3, v4
	v_readlane_b32 s5, v254, 53
	v_cmp_gt_u32_e32 vcc, 16, v4
	v_lshl_add_u64 v[20:21], s[64:65], 0, v[2:3]
	v_lshl_add_u64 v[22:23], s[58:59], 0, v[2:3]
	v_lshl_add_u64 v[24:25], s[4:5], 0, v[0:1]
	v_lshl_add_u32 v26, s2, 4, v5
	s_lshl_b32 s3, s38, 4
	s_mov_b32 s4, 0x3a800000
	s_mov_b32 s5, 0x800000
	v_mov_b32_e32 v28, 0x358637bd
	v_readlane_b32 s6, v254, 54
	v_readlane_b32 s7, v254, 55
	v_readlane_b32 s8, v254, 56
	v_readlane_b32 s9, v254, 57
	v_readlane_b32 s10, v254, 58
	v_readlane_b32 s11, v254, 59
	v_readlane_b32 s12, v254, 60
	v_readlane_b32 s13, v254, 61
	v_readlane_b32 s14, v254, 62
	v_readlane_b32 s15, v254, 63
	v_readlane_b32 s16, v255, 0
	v_readlane_b32 s17, v255, 1
	v_readlane_b32 s18, v255, 2
	v_readlane_b32 s19, v255, 3
	s_branch .LBB0_1471
